# GEMM K-loops: each group of 8 independent MFMAs reordered to a snake so only one operand fragment changes between consecutive MFMAs (test of operand-toggling power effect on clock)
# speedup vs baseline: 1.0033x; 1.0017x over previous
.LBB0_193:
	s_add_u32 s38, s24, s36
	s_addc_u32 s39, s25, s37
	s_add_u32 s38, s38, 0x100
	s_addc_u32 s39, s39, 0
	s_add_u32 s92, s86, s36
	s_addc_u32 s94, s87, s37
	s_add_i32 s95, 0, 0x10000
	s_cmpk_eq_i32 s36, 0xf00
	s_cselect_b32 s79, s29, s39
	s_cselect_b32 s78, s88, s38
	v_add_u32_e32 v0, s95, v143
	s_cselect_b32 s39, s27, s94
	s_cselect_b32 s38, s89, s92
	s_add_i32 s92, 0, 0x14000
	ds_read_b128 v[146:149], v0
	ds_read_b128 v[150:153], v0 offset:1024
	ds_read_b128 v[154:157], v0 offset:2048
	ds_read_b128 v[158:161], v0 offset:3072
	v_add_u32_e32 v0, s92, v143
	ds_read_b128 v[162:165], v0
	ds_read_b128 v[166:169], v0 offset:1024
	ds_read_b128 v[170:173], v0 offset:2048
	ds_read_b128 v[174:177], v0 offset:3072
	v_lshl_add_u64 v[186:187], v[140:141], 0, s[36:37]
	s_add_i32 m0, s17, 0xc000
	ds_read_b128 v[178:181], v144
	ds_read_b128 v[182:185], v144 offset:1024
	ds_read_b128 v[192:195], v144 offset:2048
	ds_read_b128 v[196:199], v144 offset:3072
	ds_read_b128 v[208:211], v144 offset:4096
	ds_read_b128 v[212:215], v144 offset:5120
	ds_read_b128 v[216:219], v144 offset:6144
	ds_read_b128 v[226:229], v144 offset:7168
	global_load_lds_dwordx4 v[186:187], off
	v_lshl_add_u64 v[186:187], v[2:3], 0, s[36:37]
	s_add_i32 m0, s17, 0xe000
	s_nop 0
	global_load_lds_dwordx4 v[186:187], off
	s_waitcnt vmcnt(8)
	s_waitcnt lgkmcnt(0)
	s_barrier
	s_setprio 1
	s_waitcnt lgkmcnt(0)
	v_mfma_f32_16x16x32_bf16 v[64:67], v[146:149], v[178:181], v[64:67]
	v_mfma_f32_16x16x32_bf16 v[60:63], v[154:157], v[178:181], v[60:63]
	v_mfma_f32_16x16x32_bf16 v[52:55], v[154:157], v[192:195], v[52:55]
	v_mfma_f32_16x16x32_bf16 v[56:59], v[146:149], v[192:195], v[56:59]
	v_mfma_f32_16x16x32_bf16 v[48:51], v[146:149], v[208:211], v[48:51]
	v_mfma_f32_16x16x32_bf16 v[44:47], v[154:157], v[208:211], v[44:47]
	v_mfma_f32_16x16x32_bf16 v[36:39], v[154:157], v[216:219], v[36:39]
	v_mfma_f32_16x16x32_bf16 v[40:43], v[146:149], v[216:219], v[40:43]
	v_mfma_f32_16x16x32_bf16 v[64:67], v[150:153], v[182:185], v[64:67]
	v_mfma_f32_16x16x32_bf16 v[60:63], v[158:161], v[182:185], v[60:63]
	v_mfma_f32_16x16x32_bf16 v[52:55], v[158:161], v[196:199], v[52:55]
	v_mfma_f32_16x16x32_bf16 v[56:59], v[150:153], v[196:199], v[56:59]
	v_mfma_f32_16x16x32_bf16 v[48:51], v[150:153], v[212:215], v[48:51]
	v_mfma_f32_16x16x32_bf16 v[44:47], v[158:161], v[212:215], v[44:47]
	v_mfma_f32_16x16x32_bf16 v[36:39], v[158:161], v[226:229], v[36:39]
	v_mfma_f32_16x16x32_bf16 v[40:43], v[150:153], v[226:229], v[40:43]
	s_setprio 0
	s_setprio 1
	v_mfma_f32_16x16x32_bf16 v[128:131], v[162:165], v[178:181], v[128:131]
	v_mfma_f32_16x16x32_bf16 v[124:127], v[170:173], v[178:181], v[124:127]
	v_mfma_f32_16x16x32_bf16 v[116:119], v[170:173], v[192:195], v[116:119]
	v_mfma_f32_16x16x32_bf16 v[120:123], v[162:165], v[192:195], v[120:123]
	v_mfma_f32_16x16x32_bf16 v[112:115], v[162:165], v[208:211], v[112:115]
	v_mfma_f32_16x16x32_bf16 v[108:111], v[170:173], v[208:211], v[108:111]
	v_mfma_f32_16x16x32_bf16 v[100:103], v[170:173], v[216:219], v[100:103]
	v_mfma_f32_16x16x32_bf16 v[104:107], v[162:165], v[216:219], v[104:107]
	v_mfma_f32_16x16x32_bf16 v[128:131], v[166:169], v[182:185], v[128:131]
	v_mfma_f32_16x16x32_bf16 v[124:127], v[174:177], v[182:185], v[124:127]
	v_mfma_f32_16x16x32_bf16 v[116:119], v[174:177], v[196:199], v[116:119]
	v_mfma_f32_16x16x32_bf16 v[120:123], v[166:169], v[196:199], v[120:123]
	v_mfma_f32_16x16x32_bf16 v[112:115], v[166:169], v[212:215], v[112:115]
	v_mfma_f32_16x16x32_bf16 v[108:111], v[174:177], v[212:215], v[108:111]
	v_mfma_f32_16x16x32_bf16 v[100:103], v[174:177], v[226:229], v[100:103]
	v_mfma_f32_16x16x32_bf16 v[104:107], v[166:169], v[226:229], v[104:107]
	s_setprio 0
	s_barrier
	s_add_i32 s94, s95, s65
	v_lshl_add_u64 v[186:187], s[38:39], 0, v[134:135]
	s_mov_b32 m0, s94
	ds_read_b128 v[178:181], v144 offset:16384
	ds_read_b128 v[182:185], v144 offset:17408
	ds_read_b128 v[192:195], v144 offset:18432
	ds_read_b128 v[196:199], v144 offset:19456
	ds_read_b128 v[208:211], v144 offset:20480
	ds_read_b128 v[212:215], v144 offset:21504
	ds_read_b128 v[216:219], v144 offset:22528
	ds_read_b128 v[226:229], v144 offset:23552
	global_load_lds_dwordx4 v[186:187], off
	s_add_i32 m0, s94, 0x2000
	s_add_u32 s94, s38, 0x80000
	v_lshl_add_u64 v[200:201], s[38:39], 0, v[132:133]
	s_addc_u32 s95, s39, 0
	s_add_i32 s92, s92, s65
	global_load_lds_dwordx4 v[200:201], off
	v_lshl_add_u64 v[202:203], s[94:95], 0, v[134:135]
	s_mov_b32 m0, s92
	v_lshl_add_u64 v[204:205], s[78:79], 0, v[132:133]
	global_load_lds_dwordx4 v[202:203], off
	v_lshl_add_u64 v[202:203], s[94:95], 0, v[132:133]
	s_add_i32 m0, s92, 0x2000
	s_nop 0
	global_load_lds_dwordx4 v[202:203], off
	v_lshl_add_u64 v[202:203], s[78:79], 0, v[134:135]
	s_mov_b32 m0, s17
	s_nop 0
	global_load_lds_dwordx4 v[202:203], off
	s_mov_b32 m0, s69
	s_nop 0
	global_load_lds_dwordx4 v[204:205], off
	s_waitcnt vmcnt(8)
	s_waitcnt lgkmcnt(0)
	s_barrier
	s_setprio 1
	s_waitcnt lgkmcnt(0)
	v_mfma_f32_16x16x32_bf16 v[32:35], v[146:149], v[178:181], v[32:35]
	v_mfma_f32_16x16x32_bf16 v[28:31], v[154:157], v[178:181], v[28:31]
	v_mfma_f32_16x16x32_bf16 v[20:23], v[154:157], v[192:195], v[20:23]
	v_mfma_f32_16x16x32_bf16 v[24:27], v[146:149], v[192:195], v[24:27]
	v_mfma_f32_16x16x32_bf16 v[16:19], v[146:149], v[208:211], v[16:19]
	v_mfma_f32_16x16x32_bf16 v[12:15], v[154:157], v[208:211], v[12:15]
	v_mfma_f32_16x16x32_bf16 v[4:7], v[154:157], v[216:219], v[4:7]
	v_mfma_f32_16x16x32_bf16 v[8:11], v[146:149], v[216:219], v[8:11]
	v_mfma_f32_16x16x32_bf16 v[32:35], v[150:153], v[182:185], v[32:35]
	v_mfma_f32_16x16x32_bf16 v[28:31], v[158:161], v[182:185], v[28:31]
	v_mfma_f32_16x16x32_bf16 v[20:23], v[158:161], v[196:199], v[20:23]
	v_mfma_f32_16x16x32_bf16 v[24:27], v[150:153], v[196:199], v[24:27]
	v_mfma_f32_16x16x32_bf16 v[16:19], v[150:153], v[212:215], v[16:19]
	v_mfma_f32_16x16x32_bf16 v[12:15], v[158:161], v[212:215], v[12:15]
	v_mfma_f32_16x16x32_bf16 v[4:7], v[158:161], v[226:229], v[4:7]
	v_mfma_f32_16x16x32_bf16 v[8:11], v[150:153], v[226:229], v[8:11]
	s_setprio 0
	s_setprio 1
	v_mfma_f32_16x16x32_bf16 v[96:99], v[162:165], v[178:181], v[96:99]
	v_mfma_f32_16x16x32_bf16 v[92:95], v[170:173], v[178:181], v[92:95]
	v_mfma_f32_16x16x32_bf16 v[84:87], v[170:173], v[192:195], v[84:87]
	v_mfma_f32_16x16x32_bf16 v[88:91], v[162:165], v[192:195], v[88:91]
	v_mfma_f32_16x16x32_bf16 v[80:83], v[162:165], v[208:211], v[80:83]
	v_mfma_f32_16x16x32_bf16 v[76:79], v[170:173], v[208:211], v[76:79]
	v_mfma_f32_16x16x32_bf16 v[68:71], v[170:173], v[216:219], v[68:71]
	v_mfma_f32_16x16x32_bf16 v[72:75], v[162:165], v[216:219], v[72:75]
	v_mfma_f32_16x16x32_bf16 v[96:99], v[166:169], v[182:185], v[96:99]
	v_mfma_f32_16x16x32_bf16 v[92:95], v[174:177], v[182:185], v[92:95]
	v_mfma_f32_16x16x32_bf16 v[84:87], v[174:177], v[196:199], v[84:87]
	v_mfma_f32_16x16x32_bf16 v[88:91], v[166:169], v[196:199], v[88:91]
	v_mfma_f32_16x16x32_bf16 v[80:83], v[166:169], v[212:215], v[80:83]
	v_mfma_f32_16x16x32_bf16 v[76:79], v[174:177], v[212:215], v[76:79]
	v_mfma_f32_16x16x32_bf16 v[68:71], v[174:177], v[226:229], v[68:71]
	v_mfma_f32_16x16x32_bf16 v[72:75], v[166:169], v[226:229], v[72:75]
	s_setprio 0
	s_barrier
	s_add_i32 s92, 0, 0x18000
	v_add_u32_e32 v0, s92, v143
	s_add_i32 s94, 0, 0x1c000
	ds_read_b128 v[146:149], v0
	ds_read_b128 v[150:153], v0 offset:1024
	ds_read_b128 v[154:157], v0 offset:2048
	ds_read_b128 v[158:161], v0 offset:3072
	v_add_u32_e32 v0, s94, v143
	ds_read_b128 v[162:165], v0
	ds_read_b128 v[166:169], v0 offset:1024
	ds_read_b128 v[170:173], v0 offset:2048
	ds_read_b128 v[174:177], v0 offset:3072
	s_add_u32 s78, s78, 0x80000
	s_addc_u32 s79, s79, 0
	s_mov_b32 m0, s70
	v_lshl_add_u64 v[206:207], s[78:79], 0, v[134:135]
	ds_read_b128 v[178:181], v144 offset:32768
	ds_read_b128 v[182:185], v144 offset:33792
	ds_read_b128 v[192:195], v144 offset:34816
	ds_read_b128 v[196:199], v144 offset:35840
	ds_read_b128 v[208:211], v144 offset:36864
	ds_read_b128 v[212:215], v144 offset:37888
	ds_read_b128 v[216:219], v144 offset:38912
	ds_read_b128 v[226:229], v144 offset:39936
	global_load_lds_dwordx4 v[206:207], off
	v_lshl_add_u64 v[206:207], s[78:79], 0, v[132:133]
	s_mov_b32 m0, s71
	s_nop 0
	global_load_lds_dwordx4 v[206:207], off
	s_waitcnt vmcnt(8)
	s_waitcnt lgkmcnt(0)
	s_barrier
	s_setprio 1
	s_waitcnt lgkmcnt(0)
	v_mfma_f32_16x16x32_bf16 v[64:67], v[146:149], v[178:181], v[64:67]
	v_mfma_f32_16x16x32_bf16 v[60:63], v[154:157], v[178:181], v[60:63]
	v_mfma_f32_16x16x32_bf16 v[52:55], v[154:157], v[192:195], v[52:55]
	v_mfma_f32_16x16x32_bf16 v[56:59], v[146:149], v[192:195], v[56:59]
	v_mfma_f32_16x16x32_bf16 v[48:51], v[146:149], v[208:211], v[48:51]
	v_mfma_f32_16x16x32_bf16 v[44:47], v[154:157], v[208:211], v[44:47]
	v_mfma_f32_16x16x32_bf16 v[36:39], v[154:157], v[216:219], v[36:39]
	v_mfma_f32_16x16x32_bf16 v[40:43], v[146:149], v[216:219], v[40:43]
	v_mfma_f32_16x16x32_bf16 v[64:67], v[150:153], v[182:185], v[64:67]
	v_mfma_f32_16x16x32_bf16 v[60:63], v[158:161], v[182:185], v[60:63]
	v_mfma_f32_16x16x32_bf16 v[52:55], v[158:161], v[196:199], v[52:55]
	v_mfma_f32_16x16x32_bf16 v[56:59], v[150:153], v[196:199], v[56:59]
	v_mfma_f32_16x16x32_bf16 v[48:51], v[150:153], v[212:215], v[48:51]
	v_mfma_f32_16x16x32_bf16 v[44:47], v[158:161], v[212:215], v[44:47]
	v_mfma_f32_16x16x32_bf16 v[36:39], v[158:161], v[226:229], v[36:39]
	v_mfma_f32_16x16x32_bf16 v[40:43], v[150:153], v[226:229], v[40:43]
	s_setprio 0
	s_setprio 1
	v_mfma_f32_16x16x32_bf16 v[128:131], v[162:165], v[178:181], v[128:131]
	v_mfma_f32_16x16x32_bf16 v[124:127], v[170:173], v[178:181], v[124:127]
	v_mfma_f32_16x16x32_bf16 v[116:119], v[170:173], v[192:195], v[116:119]
	v_mfma_f32_16x16x32_bf16 v[120:123], v[162:165], v[192:195], v[120:123]
	v_mfma_f32_16x16x32_bf16 v[112:115], v[162:165], v[208:211], v[112:115]
	v_mfma_f32_16x16x32_bf16 v[108:111], v[170:173], v[208:211], v[108:111]
	v_mfma_f32_16x16x32_bf16 v[100:103], v[170:173], v[216:219], v[100:103]
	v_mfma_f32_16x16x32_bf16 v[104:107], v[162:165], v[216:219], v[104:107]
	v_mfma_f32_16x16x32_bf16 v[128:131], v[166:169], v[182:185], v[128:131]
	v_mfma_f32_16x16x32_bf16 v[124:127], v[174:177], v[182:185], v[124:127]
	v_mfma_f32_16x16x32_bf16 v[116:119], v[174:177], v[196:199], v[116:119]
	v_mfma_f32_16x16x32_bf16 v[120:123], v[166:169], v[196:199], v[120:123]
	v_mfma_f32_16x16x32_bf16 v[112:115], v[166:169], v[212:215], v[112:115]
	v_mfma_f32_16x16x32_bf16 v[108:111], v[174:177], v[212:215], v[108:111]
	v_mfma_f32_16x16x32_bf16 v[100:103], v[174:177], v[226:229], v[100:103]
	v_mfma_f32_16x16x32_bf16 v[104:107], v[166:169], v[226:229], v[104:107]
	s_setprio 0
	s_barrier
	s_add_i32 s78, s92, s65
	v_lshl_add_u64 v[186:187], v[186:187], 0, s[54:55]
	s_mov_b32 m0, s78
	ds_read_b128 v[178:181], v144 offset:49152
	ds_read_b128 v[182:185], v144 offset:50176
	ds_read_b128 v[192:195], v144 offset:51200
	ds_read_b128 v[196:199], v144 offset:52224
	ds_read_b128 v[208:211], v144 offset:53248
	ds_read_b128 v[212:215], v144 offset:54272
	ds_read_b128 v[216:219], v144 offset:55296
	ds_read_b128 v[226:229], v144 offset:56320
	global_load_lds_dwordx4 v[186:187], off
	s_add_i32 m0, s78, 0x2000
	s_add_u32 s38, s38, 0x80080
	v_lshl_add_u64 v[186:187], v[200:201], 0, s[54:55]
	s_addc_u32 s39, s39, 0
	s_add_i32 s78, s94, s65
	global_load_lds_dwordx4 v[186:187], off
	v_lshl_add_u64 v[186:187], s[38:39], 0, v[134:135]
	s_mov_b32 m0, s78
	s_nop 0
	global_load_lds_dwordx4 v[186:187], off
	v_lshl_add_u64 v[186:187], s[38:39], 0, v[132:133]
	s_add_i32 m0, s78, 0x2000
	s_nop 0
	global_load_lds_dwordx4 v[186:187], off
	v_lshl_add_u64 v[186:187], v[202:203], 0, s[54:55]
	s_mov_b32 m0, s72
	s_nop 0
	global_load_lds_dwordx4 v[186:187], off
	v_lshl_add_u64 v[186:187], v[204:205], 0, s[54:55]
	s_mov_b32 m0, s73
	s_nop 0
	global_load_lds_dwordx4 v[186:187], off
	s_waitcnt vmcnt(8)
	s_waitcnt lgkmcnt(0)
	s_barrier
	s_setprio 1
	s_waitcnt lgkmcnt(0)
	v_mfma_f32_16x16x32_bf16 v[32:35], v[146:149], v[178:181], v[32:35]
	v_mfma_f32_16x16x32_bf16 v[28:31], v[154:157], v[178:181], v[28:31]
	v_mfma_f32_16x16x32_bf16 v[20:23], v[154:157], v[192:195], v[20:23]
	v_mfma_f32_16x16x32_bf16 v[24:27], v[146:149], v[192:195], v[24:27]
	v_mfma_f32_16x16x32_bf16 v[16:19], v[146:149], v[208:211], v[16:19]
	v_mfma_f32_16x16x32_bf16 v[12:15], v[154:157], v[208:211], v[12:15]
	v_mfma_f32_16x16x32_bf16 v[4:7], v[154:157], v[216:219], v[4:7]
	v_mfma_f32_16x16x32_bf16 v[8:11], v[146:149], v[216:219], v[8:11]
	v_mfma_f32_16x16x32_bf16 v[32:35], v[150:153], v[182:185], v[32:35]
	v_mfma_f32_16x16x32_bf16 v[28:31], v[158:161], v[182:185], v[28:31]
	v_mfma_f32_16x16x32_bf16 v[20:23], v[158:161], v[196:199], v[20:23]
	v_mfma_f32_16x16x32_bf16 v[24:27], v[150:153], v[196:199], v[24:27]
	v_mfma_f32_16x16x32_bf16 v[16:19], v[150:153], v[212:215], v[16:19]
	v_mfma_f32_16x16x32_bf16 v[12:15], v[158:161], v[212:215], v[12:15]
	v_mfma_f32_16x16x32_bf16 v[4:7], v[158:161], v[226:229], v[4:7]
	v_mfma_f32_16x16x32_bf16 v[8:11], v[150:153], v[226:229], v[8:11]
	s_setprio 0
	s_setprio 1
	v_mfma_f32_16x16x32_bf16 v[96:99], v[162:165], v[178:181], v[96:99]
	v_mfma_f32_16x16x32_bf16 v[92:95], v[170:173], v[178:181], v[92:95]
	v_mfma_f32_16x16x32_bf16 v[84:87], v[170:173], v[192:195], v[84:87]
	v_mfma_f32_16x16x32_bf16 v[88:91], v[162:165], v[192:195], v[88:91]
	v_mfma_f32_16x16x32_bf16 v[80:83], v[162:165], v[208:211], v[80:83]
	v_mfma_f32_16x16x32_bf16 v[76:79], v[170:173], v[208:211], v[76:79]
	v_mfma_f32_16x16x32_bf16 v[68:71], v[170:173], v[216:219], v[68:71]
	v_mfma_f32_16x16x32_bf16 v[72:75], v[162:165], v[216:219], v[72:75]
	v_mfma_f32_16x16x32_bf16 v[96:99], v[166:169], v[182:185], v[96:99]
	v_mfma_f32_16x16x32_bf16 v[92:95], v[174:177], v[182:185], v[92:95]
	v_mfma_f32_16x16x32_bf16 v[84:87], v[174:177], v[196:199], v[84:87]
	v_mfma_f32_16x16x32_bf16 v[88:91], v[166:169], v[196:199], v[88:91]
	v_mfma_f32_16x16x32_bf16 v[80:83], v[166:169], v[212:215], v[80:83]
	v_mfma_f32_16x16x32_bf16 v[76:79], v[174:177], v[212:215], v[76:79]
	v_mfma_f32_16x16x32_bf16 v[68:71], v[174:177], v[226:229], v[68:71]
	v_mfma_f32_16x16x32_bf16 v[72:75], v[166:169], v[226:229], v[72:75]
	s_setprio 0
	s_barrier
	s_add_i32 s93, s93, 2
	s_add_u32 s36, s36, 0x100
	s_addc_u32 s37, s37, 0
	s_cmp_gt_u32 s93, 29
	s_cbranch_scc0 .LBB0_193
	s_add_u32 s36, s86, 0xffffff00
	s_addc_u32 s37, s87, -1
	s_andn2_b64 vcc, exec, s[8:9]
	s_cbranch_vccnz .LBB0_196
	v_mov_b32_e32 v2, v1
	v_mov_b32_e32 v3, v1
	v_mov_b32_e32 v0, v1
	v_mov_b32_e32 v68, 0
	v_mov_b64_e32 v[6:7], v[2:3]
	v_mov_b64_e32 v[10:11], v[2:3]
	v_mov_b64_e32 v[14:15], v[2:3]
	v_mov_b64_e32 v[18:19], v[2:3]
	v_mov_b64_e32 v[22:23], v[2:3]
	v_mov_b64_e32 v[26:27], v[2:3]
	v_mov_b64_e32 v[30:31], v[2:3]
	v_mov_b64_e32 v[34:35], v[2:3]
	v_mov_b64_e32 v[38:39], v[2:3]
	v_mov_b64_e32 v[42:43], v[2:3]
	v_mov_b64_e32 v[46:47], v[2:3]
	v_mov_b64_e32 v[50:51], v[2:3]
	v_mov_b64_e32 v[54:55], v[2:3]
	v_mov_b64_e32 v[58:59], v[2:3]
	v_mov_b64_e32 v[62:63], v[2:3]
	v_mov_b64_e32 v[66:67], v[2:3]
	v_mov_b64_e32 v[4:5], v[0:1]
	v_mov_b64_e32 v[8:9], v[0:1]
	v_mov_b64_e32 v[12:13], v[0:1]
	v_mov_b64_e32 v[16:17], v[0:1]
	v_mov_b64_e32 v[20:21], v[0:1]
	v_mov_b64_e32 v[24:25], v[0:1]
	v_mov_b64_e32 v[28:29], v[0:1]
	v_mov_b64_e32 v[32:33], v[0:1]
	v_mov_b64_e32 v[36:37], v[0:1]
	v_mov_b64_e32 v[40:41], v[0:1]
	v_mov_b64_e32 v[44:45], v[0:1]
	v_mov_b64_e32 v[48:49], v[0:1]
	v_mov_b64_e32 v[52:53], v[0:1]
	v_mov_b64_e32 v[56:57], v[0:1]
	v_mov_b64_e32 v[60:61], v[0:1]
	v_mov_b64_e32 v[64:65], v[0:1]
	s_mov_b32 s22, s26
	s_mov_b32 s16, s28
	s_mov_b64 s[24:25], s[34:35]
	s_mov_b32 s84, s85
	v_mov_b32_e32 v69, v68
	v_mov_b32_e32 v70, v68
	v_mov_b32_e32 v71, v68
	v_mov_b32_e32 v72, v68
	v_mov_b32_e32 v73, v68
	v_mov_b32_e32 v74, v68
	v_mov_b32_e32 v75, v68
	v_mov_b32_e32 v76, v68
	v_mov_b32_e32 v77, v68
	v_mov_b32_e32 v78, v68
	v_mov_b32_e32 v79, v68
	v_mov_b32_e32 v80, v68
	v_mov_b32_e32 v81, v68
	v_mov_b32_e32 v82, v68
	v_mov_b32_e32 v83, v68
	v_mov_b32_e32 v84, v68
	v_mov_b32_e32 v85, v68
	v_mov_b32_e32 v86, v68
	v_mov_b32_e32 v87, v68
	v_mov_b32_e32 v88, v68
	v_mov_b32_e32 v89, v68
	v_mov_b32_e32 v90, v68
	v_mov_b32_e32 v91, v68
	v_mov_b32_e32 v92, v68
	v_mov_b32_e32 v93, v68
	v_mov_b32_e32 v94, v68
	v_mov_b32_e32 v95, v68
	v_mov_b32_e32 v96, v68
	v_mov_b32_e32 v97, v68
	v_mov_b32_e32 v98, v68
	v_mov_b32_e32 v99, v68
	v_mov_b32_e32 v100, v68
	v_mov_b32_e32 v101, v68
	v_mov_b32_e32 v102, v68
	v_mov_b32_e32 v103, v68
	v_mov_b32_e32 v104, v68
	v_mov_b32_e32 v105, v68
	v_mov_b32_e32 v106, v68
	v_mov_b32_e32 v107, v68
	v_mov_b32_e32 v108, v68
	v_mov_b32_e32 v109, v68
	v_mov_b32_e32 v110, v68
	v_mov_b32_e32 v111, v68
	v_mov_b32_e32 v112, v68
	v_mov_b32_e32 v113, v68
	v_mov_b32_e32 v114, v68
	v_mov_b32_e32 v115, v68
	v_mov_b32_e32 v116, v68
	v_mov_b32_e32 v117, v68
	v_mov_b32_e32 v118, v68
	v_mov_b32_e32 v119, v68
	v_mov_b32_e32 v120, v68
	v_mov_b32_e32 v121, v68
	v_mov_b32_e32 v122, v68
	v_mov_b32_e32 v123, v68
	v_mov_b32_e32 v124, v68
	v_mov_b32_e32 v125, v68
	v_mov_b32_e32 v126, v68
	v_mov_b32_e32 v127, v68
	v_mov_b32_e32 v128, v68
	v_mov_b32_e32 v129, v68
	v_mov_b32_e32 v130, v68
	v_mov_b32_e32 v131, v68
	s_andn2_b64 vcc, exec, s[6:7]
	s_cbranch_vccnz .LBB0_197
	s_branch .LBB0_198

.LBB0_430:
	s_add_u32 s36, s34, 0xfffe0080
	s_addc_u32 s37, s35, -1
	s_add_i32 s49, 0, 0x10000
	s_cmp_eq_u32 s48, 4
	s_cselect_b32 s39, s7, s37
	s_cselect_b32 s38, s9, s36
	s_cselect_b32 s37, s21, s45
	s_cselect_b32 s36, s25, s27
	s_add_i32 s61, 0, 0x14000
	v_add_u32_e32 v142, s49, v216
	v_add_u32_e32 v158, s61, v216
	ds_read_b128 v[130:133], v142
	ds_read_b128 v[134:137], v142 offset:1024
	ds_read_b128 v[138:141], v142 offset:2048
	ds_read_b128 v[142:145], v142 offset:3072
	ds_read_b128 v[146:149], v158
	ds_read_b128 v[150:153], v158 offset:1024
	ds_read_b128 v[154:157], v158 offset:2048
	ds_read_b128 v[158:161], v158 offset:3072
	v_lshl_add_u64 v[202:203], s[34:35], 0, v[210:211]
	s_add_i32 m0, s87, 0xc000
	ds_read_b128 v[162:165], v221
	ds_read_b128 v[166:169], v221 offset:1024
	ds_read_b128 v[170:173], v221 offset:2048
	ds_read_b128 v[174:177], v221 offset:3072
	ds_read_b128 v[178:181], v221 offset:4096
	ds_read_b128 v[182:185], v221 offset:5120
	ds_read_b128 v[186:189], v221 offset:6144
	ds_read_b128 v[190:193], v221 offset:7168
	global_load_lds_dwordx4 v[202:203], off
	v_lshl_add_u64 v[202:203], s[34:35], 0, v[208:209]
	s_add_i32 m0, s87, 0xe000
	s_nop 0
	global_load_lds_dwordx4 v[202:203], off
	s_waitcnt vmcnt(8)
	s_waitcnt lgkmcnt(0)
	s_barrier
	s_setprio 1
	s_waitcnt lgkmcnt(0)
	v_mfma_f32_16x16x32_bf16 v[126:129], v[130:133], v[162:165], v[126:129]
	v_mfma_f32_16x16x32_bf16 v[122:125], v[138:141], v[162:165], v[122:125]
	v_mfma_f32_16x16x32_bf16 v[106:109], v[138:141], v[170:173], v[106:109]
	v_mfma_f32_16x16x32_bf16 v[110:113], v[130:133], v[170:173], v[110:113]
	v_mfma_f32_16x16x32_bf16 v[94:97], v[130:133], v[178:181], v[94:97]
	v_mfma_f32_16x16x32_bf16 v[90:93], v[138:141], v[178:181], v[90:93]
	v_mfma_f32_16x16x32_bf16 v[74:77], v[138:141], v[186:189], v[74:77]
	v_mfma_f32_16x16x32_bf16 v[78:81], v[130:133], v[186:189], v[78:81]
	v_mfma_f32_16x16x32_bf16 v[126:129], v[134:137], v[166:169], v[126:129]
	v_mfma_f32_16x16x32_bf16 v[122:125], v[142:145], v[166:169], v[122:125]
	v_mfma_f32_16x16x32_bf16 v[106:109], v[142:145], v[174:177], v[106:109]
	v_mfma_f32_16x16x32_bf16 v[110:113], v[134:137], v[174:177], v[110:113]
	v_mfma_f32_16x16x32_bf16 v[94:97], v[134:137], v[182:185], v[94:97]
	v_mfma_f32_16x16x32_bf16 v[90:93], v[142:145], v[182:185], v[90:93]
	v_mfma_f32_16x16x32_bf16 v[74:77], v[142:145], v[190:193], v[74:77]
	v_mfma_f32_16x16x32_bf16 v[78:81], v[134:137], v[190:193], v[78:81]
	s_setprio 0
	s_setprio 1
	v_mfma_f32_16x16x32_bf16 v[118:121], v[146:149], v[162:165], v[118:121]
	v_mfma_f32_16x16x32_bf16 v[114:117], v[154:157], v[162:165], v[114:117]
	v_mfma_f32_16x16x32_bf16 v[98:101], v[154:157], v[170:173], v[98:101]
	v_mfma_f32_16x16x32_bf16 v[102:105], v[146:149], v[170:173], v[102:105]
	v_mfma_f32_16x16x32_bf16 v[86:89], v[146:149], v[178:181], v[86:89]
	v_mfma_f32_16x16x32_bf16 v[82:85], v[154:157], v[178:181], v[82:85]
	v_mfma_f32_16x16x32_bf16 v[66:69], v[154:157], v[186:189], v[66:69]
	v_mfma_f32_16x16x32_bf16 v[70:73], v[146:149], v[186:189], v[70:73]
	v_mfma_f32_16x16x32_bf16 v[118:121], v[150:153], v[166:169], v[118:121]
	v_mfma_f32_16x16x32_bf16 v[114:117], v[158:161], v[166:169], v[114:117]
	v_mfma_f32_16x16x32_bf16 v[98:101], v[158:161], v[174:177], v[98:101]
	v_mfma_f32_16x16x32_bf16 v[102:105], v[150:153], v[174:177], v[102:105]
	v_mfma_f32_16x16x32_bf16 v[86:89], v[150:153], v[182:185], v[86:89]
	v_mfma_f32_16x16x32_bf16 v[82:85], v[158:161], v[182:185], v[82:85]
	v_mfma_f32_16x16x32_bf16 v[66:69], v[158:161], v[190:193], v[66:69]
	v_mfma_f32_16x16x32_bf16 v[70:73], v[150:153], v[190:193], v[70:73]
	s_setprio 0
	s_barrier
	s_add_i32 s49, s49, s86
	v_lshl_add_u64 v[202:203], s[36:37], 0, v[194:195]
	s_mov_b32 m0, s49
	ds_read_b128 v[162:165], v221 offset:16384
	ds_read_b128 v[166:169], v221 offset:17408
	ds_read_b128 v[170:173], v221 offset:18432
	ds_read_b128 v[174:177], v221 offset:19456
	ds_read_b128 v[178:181], v221 offset:20480
	ds_read_b128 v[182:185], v221 offset:21504
	ds_read_b128 v[186:189], v221 offset:22528
	ds_read_b128 v[190:193], v221 offset:23552
	global_load_lds_dwordx4 v[202:203], off
	s_add_i32 m0, s49, 0x2000
	s_add_u32 s94, s36, 0x20000
	v_lshl_add_u64 v[204:205], s[36:37], 0, v[196:197]
	s_addc_u32 s95, s37, 0
	s_add_i32 s49, s61, s86
	global_load_lds_dwordx4 v[204:205], off
	v_lshl_add_u64 v[206:207], s[94:95], 0, v[194:195]
	s_mov_b32 m0, s49
	v_lshl_add_u64 v[222:223], s[38:39], 0, v[196:197]
	global_load_lds_dwordx4 v[206:207], off
	v_lshl_add_u64 v[206:207], s[94:95], 0, v[196:197]
	s_add_i32 m0, s49, 0x2000
	s_nop 0
	global_load_lds_dwordx4 v[206:207], off
	v_lshl_add_u64 v[206:207], s[38:39], 0, v[194:195]
	s_mov_b32 m0, s87
	s_nop 0
	global_load_lds_dwordx4 v[206:207], off
	s_mov_b32 m0, s68
	s_nop 0
	global_load_lds_dwordx4 v[222:223], off
	s_waitcnt vmcnt(8)
	s_waitcnt lgkmcnt(0)
	s_barrier
	s_setprio 1
	s_waitcnt lgkmcnt(0)
	v_mfma_f32_16x16x32_bf16 v[62:65], v[130:133], v[162:165], v[62:65]
	v_mfma_f32_16x16x32_bf16 v[58:61], v[138:141], v[162:165], v[58:61]
	v_mfma_f32_16x16x32_bf16 v[42:45], v[138:141], v[170:173], v[42:45]
	v_mfma_f32_16x16x32_bf16 v[46:49], v[130:133], v[170:173], v[46:49]
	v_mfma_f32_16x16x32_bf16 v[30:33], v[130:133], v[178:181], v[30:33]
	v_mfma_f32_16x16x32_bf16 v[26:29], v[138:141], v[178:181], v[26:29]
	v_mfma_f32_16x16x32_bf16 v[10:13], v[138:141], v[186:189], v[10:13]
	v_mfma_f32_16x16x32_bf16 v[14:17], v[130:133], v[186:189], v[14:17]
	v_mfma_f32_16x16x32_bf16 v[62:65], v[134:137], v[166:169], v[62:65]
	v_mfma_f32_16x16x32_bf16 v[58:61], v[142:145], v[166:169], v[58:61]
	v_mfma_f32_16x16x32_bf16 v[42:45], v[142:145], v[174:177], v[42:45]
	v_mfma_f32_16x16x32_bf16 v[46:49], v[134:137], v[174:177], v[46:49]
	v_mfma_f32_16x16x32_bf16 v[30:33], v[134:137], v[182:185], v[30:33]
	v_mfma_f32_16x16x32_bf16 v[26:29], v[142:145], v[182:185], v[26:29]
	v_mfma_f32_16x16x32_bf16 v[10:13], v[142:145], v[190:193], v[10:13]
	v_mfma_f32_16x16x32_bf16 v[14:17], v[134:137], v[190:193], v[14:17]
	s_setprio 0
	s_setprio 1
	v_mfma_f32_16x16x32_bf16 v[54:57], v[146:149], v[162:165], v[54:57]
	v_mfma_f32_16x16x32_bf16 v[50:53], v[154:157], v[162:165], v[50:53]
	v_mfma_f32_16x16x32_bf16 v[34:37], v[154:157], v[170:173], v[34:37]
	v_mfma_f32_16x16x32_bf16 v[38:41], v[146:149], v[170:173], v[38:41]
	v_mfma_f32_16x16x32_bf16 v[22:25], v[146:149], v[178:181], v[22:25]
	v_mfma_f32_16x16x32_bf16 v[18:21], v[154:157], v[178:181], v[18:21]
	v_mfma_f32_16x16x32_bf16 v[2:5], v[154:157], v[186:189], v[2:5]
	v_mfma_f32_16x16x32_bf16 v[6:9], v[146:149], v[186:189], v[6:9]
	v_mfma_f32_16x16x32_bf16 v[54:57], v[150:153], v[166:169], v[54:57]
	v_mfma_f32_16x16x32_bf16 v[50:53], v[158:161], v[166:169], v[50:53]
	v_mfma_f32_16x16x32_bf16 v[34:37], v[158:161], v[174:177], v[34:37]
	v_mfma_f32_16x16x32_bf16 v[38:41], v[150:153], v[174:177], v[38:41]
	v_mfma_f32_16x16x32_bf16 v[22:25], v[150:153], v[182:185], v[22:25]
	v_mfma_f32_16x16x32_bf16 v[18:21], v[158:161], v[182:185], v[18:21]
	v_mfma_f32_16x16x32_bf16 v[2:5], v[158:161], v[190:193], v[2:5]
	v_mfma_f32_16x16x32_bf16 v[6:9], v[150:153], v[190:193], v[6:9]
	s_setprio 0
	s_barrier
	s_add_i32 s49, 0, 0x18000
	s_add_i32 s61, 0, 0x1c000
	v_add_u32_e32 v142, s49, v216
	v_add_u32_e32 v158, s61, v216
	ds_read_b128 v[130:133], v142
	ds_read_b128 v[134:137], v142 offset:1024
	ds_read_b128 v[138:141], v142 offset:2048
	ds_read_b128 v[142:145], v142 offset:3072
	ds_read_b128 v[146:149], v158
	ds_read_b128 v[150:153], v158 offset:1024
	ds_read_b128 v[154:157], v158 offset:2048
	ds_read_b128 v[158:161], v158 offset:3072
	s_add_u32 s38, s38, 0x20000
	s_addc_u32 s39, s39, 0
	s_mov_b32 m0, s69
	v_lshl_add_u64 v[226:227], s[38:39], 0, v[194:195]
	ds_read_b128 v[162:165], v221 offset:32768
	ds_read_b128 v[166:169], v221 offset:33792
	ds_read_b128 v[170:173], v221 offset:34816
	ds_read_b128 v[174:177], v221 offset:35840
	ds_read_b128 v[178:181], v221 offset:36864
	ds_read_b128 v[182:185], v221 offset:37888
	ds_read_b128 v[186:189], v221 offset:38912
	ds_read_b128 v[190:193], v221 offset:39936
	global_load_lds_dwordx4 v[226:227], off
	v_lshl_add_u64 v[226:227], s[38:39], 0, v[196:197]
	s_mov_b32 m0, s70
	s_nop 0
	global_load_lds_dwordx4 v[226:227], off
	s_waitcnt vmcnt(8)
	s_waitcnt lgkmcnt(0)
	s_barrier
	s_setprio 1
	s_waitcnt lgkmcnt(0)
	v_mfma_f32_16x16x32_bf16 v[126:129], v[130:133], v[162:165], v[126:129]
	v_mfma_f32_16x16x32_bf16 v[122:125], v[138:141], v[162:165], v[122:125]
	v_mfma_f32_16x16x32_bf16 v[106:109], v[138:141], v[170:173], v[106:109]
	v_mfma_f32_16x16x32_bf16 v[110:113], v[130:133], v[170:173], v[110:113]
	v_mfma_f32_16x16x32_bf16 v[94:97], v[130:133], v[178:181], v[94:97]
	v_mfma_f32_16x16x32_bf16 v[90:93], v[138:141], v[178:181], v[90:93]
	v_mfma_f32_16x16x32_bf16 v[74:77], v[138:141], v[186:189], v[74:77]
	v_mfma_f32_16x16x32_bf16 v[78:81], v[130:133], v[186:189], v[78:81]
	v_mfma_f32_16x16x32_bf16 v[126:129], v[134:137], v[166:169], v[126:129]
	v_mfma_f32_16x16x32_bf16 v[122:125], v[142:145], v[166:169], v[122:125]
	v_mfma_f32_16x16x32_bf16 v[106:109], v[142:145], v[174:177], v[106:109]
	v_mfma_f32_16x16x32_bf16 v[110:113], v[134:137], v[174:177], v[110:113]
	v_mfma_f32_16x16x32_bf16 v[94:97], v[134:137], v[182:185], v[94:97]
	v_mfma_f32_16x16x32_bf16 v[90:93], v[142:145], v[182:185], v[90:93]
	v_mfma_f32_16x16x32_bf16 v[74:77], v[142:145], v[190:193], v[74:77]
	v_mfma_f32_16x16x32_bf16 v[78:81], v[134:137], v[190:193], v[78:81]
	s_setprio 0
	s_setprio 1
	v_mfma_f32_16x16x32_bf16 v[118:121], v[146:149], v[162:165], v[118:121]
	v_mfma_f32_16x16x32_bf16 v[114:117], v[154:157], v[162:165], v[114:117]
	v_mfma_f32_16x16x32_bf16 v[98:101], v[154:157], v[170:173], v[98:101]
	v_mfma_f32_16x16x32_bf16 v[102:105], v[146:149], v[170:173], v[102:105]
	v_mfma_f32_16x16x32_bf16 v[86:89], v[146:149], v[178:181], v[86:89]
	v_mfma_f32_16x16x32_bf16 v[82:85], v[154:157], v[178:181], v[82:85]
	v_mfma_f32_16x16x32_bf16 v[66:69], v[154:157], v[186:189], v[66:69]
	v_mfma_f32_16x16x32_bf16 v[70:73], v[146:149], v[186:189], v[70:73]
	v_mfma_f32_16x16x32_bf16 v[118:121], v[150:153], v[166:169], v[118:121]
	v_mfma_f32_16x16x32_bf16 v[114:117], v[158:161], v[166:169], v[114:117]
	v_mfma_f32_16x16x32_bf16 v[98:101], v[158:161], v[174:177], v[98:101]
	v_mfma_f32_16x16x32_bf16 v[102:105], v[150:153], v[174:177], v[102:105]
	v_mfma_f32_16x16x32_bf16 v[86:89], v[150:153], v[182:185], v[86:89]
	v_mfma_f32_16x16x32_bf16 v[82:85], v[158:161], v[182:185], v[82:85]
	v_mfma_f32_16x16x32_bf16 v[66:69], v[158:161], v[190:193], v[66:69]
	v_mfma_f32_16x16x32_bf16 v[70:73], v[150:153], v[190:193], v[70:73]
	s_setprio 0
	s_barrier
	s_add_i32 s38, s49, s86
	v_lshl_add_u64 v[202:203], v[202:203], 0, s[54:55]
	s_mov_b32 m0, s38
	ds_read_b128 v[162:165], v221 offset:49152
	ds_read_b128 v[166:169], v221 offset:50176
	ds_read_b128 v[170:173], v221 offset:51200
	ds_read_b128 v[174:177], v221 offset:52224
	ds_read_b128 v[178:181], v221 offset:53248
	ds_read_b128 v[182:185], v221 offset:54272
	ds_read_b128 v[186:189], v221 offset:55296
	ds_read_b128 v[190:193], v221 offset:56320
	global_load_lds_dwordx4 v[202:203], off
	s_add_i32 m0, s38, 0x2000
	s_add_u32 s36, s36, 0x20080
	v_lshl_add_u64 v[202:203], v[204:205], 0, s[54:55]
	s_addc_u32 s37, s37, 0
	s_add_i32 s38, s61, s86
	global_load_lds_dwordx4 v[202:203], off
	v_lshl_add_u64 v[202:203], s[36:37], 0, v[194:195]
	s_mov_b32 m0, s38
	s_nop 0
	global_load_lds_dwordx4 v[202:203], off
	v_lshl_add_u64 v[202:203], s[36:37], 0, v[196:197]
	s_add_i32 m0, s38, 0x2000
	s_nop 0
	global_load_lds_dwordx4 v[202:203], off
	v_lshl_add_u64 v[202:203], v[206:207], 0, s[54:55]
	s_mov_b32 m0, s73
	s_nop 0
	global_load_lds_dwordx4 v[202:203], off
	v_lshl_add_u64 v[202:203], v[222:223], 0, s[54:55]
	s_mov_b32 m0, s89
	s_nop 0
	global_load_lds_dwordx4 v[202:203], off
	s_waitcnt vmcnt(8)
	s_waitcnt lgkmcnt(0)
	s_barrier
	s_setprio 1
	s_waitcnt lgkmcnt(0)
	v_mfma_f32_16x16x32_bf16 v[62:65], v[130:133], v[162:165], v[62:65]
	v_mfma_f32_16x16x32_bf16 v[58:61], v[138:141], v[162:165], v[58:61]
	v_mfma_f32_16x16x32_bf16 v[42:45], v[138:141], v[170:173], v[42:45]
	v_mfma_f32_16x16x32_bf16 v[46:49], v[130:133], v[170:173], v[46:49]
	v_mfma_f32_16x16x32_bf16 v[30:33], v[130:133], v[178:181], v[30:33]
	v_mfma_f32_16x16x32_bf16 v[26:29], v[138:141], v[178:181], v[26:29]
	v_mfma_f32_16x16x32_bf16 v[10:13], v[138:141], v[186:189], v[10:13]
	v_mfma_f32_16x16x32_bf16 v[14:17], v[130:133], v[186:189], v[14:17]
	v_mfma_f32_16x16x32_bf16 v[62:65], v[134:137], v[166:169], v[62:65]
	v_mfma_f32_16x16x32_bf16 v[58:61], v[142:145], v[166:169], v[58:61]
	v_mfma_f32_16x16x32_bf16 v[42:45], v[142:145], v[174:177], v[42:45]
	v_mfma_f32_16x16x32_bf16 v[46:49], v[134:137], v[174:177], v[46:49]
	v_mfma_f32_16x16x32_bf16 v[30:33], v[134:137], v[182:185], v[30:33]
	v_mfma_f32_16x16x32_bf16 v[26:29], v[142:145], v[182:185], v[26:29]
	v_mfma_f32_16x16x32_bf16 v[10:13], v[142:145], v[190:193], v[10:13]
	v_mfma_f32_16x16x32_bf16 v[14:17], v[134:137], v[190:193], v[14:17]
	s_setprio 0
	s_setprio 1
	v_mfma_f32_16x16x32_bf16 v[54:57], v[146:149], v[162:165], v[54:57]
	v_mfma_f32_16x16x32_bf16 v[50:53], v[154:157], v[162:165], v[50:53]
	v_mfma_f32_16x16x32_bf16 v[34:37], v[154:157], v[170:173], v[34:37]
	v_mfma_f32_16x16x32_bf16 v[38:41], v[146:149], v[170:173], v[38:41]
	v_mfma_f32_16x16x32_bf16 v[22:25], v[146:149], v[178:181], v[22:25]
	v_mfma_f32_16x16x32_bf16 v[18:21], v[154:157], v[178:181], v[18:21]
	v_mfma_f32_16x16x32_bf16 v[2:5], v[154:157], v[186:189], v[2:5]
	v_mfma_f32_16x16x32_bf16 v[6:9], v[146:149], v[186:189], v[6:9]
	v_mfma_f32_16x16x32_bf16 v[54:57], v[150:153], v[166:169], v[54:57]
	v_mfma_f32_16x16x32_bf16 v[50:53], v[158:161], v[166:169], v[50:53]
	v_mfma_f32_16x16x32_bf16 v[34:37], v[158:161], v[174:177], v[34:37]
	v_mfma_f32_16x16x32_bf16 v[38:41], v[150:153], v[174:177], v[38:41]
	v_mfma_f32_16x16x32_bf16 v[22:25], v[150:153], v[182:185], v[22:25]
	v_mfma_f32_16x16x32_bf16 v[18:21], v[158:161], v[182:185], v[18:21]
	v_mfma_f32_16x16x32_bf16 v[2:5], v[158:161], v[190:193], v[2:5]
	v_mfma_f32_16x16x32_bf16 v[6:9], v[150:153], v[190:193], v[6:9]
	s_setprio 0
	s_barrier
	s_add_i32 s48, s48, 2
	s_add_u32 s27, s27, 0x100
	s_addc_u32 s45, s45, 0
	s_add_u32 s34, s34, 0x100
	s_addc_u32 s35, s35, 0
	s_cmp_gt_u32 s48, 5
	s_cbranch_scc0 .LBB0_430
	s_and_b64 vcc, exec, s[18:19]
	s_cbranch_vccz .LBB0_433
	s_barrier

.LBB0_605:
	s_add_u32 s80, s8, 0xfff80080
	s_addc_u32 s81, s9, -1
	s_add_i32 s87, 0, 0x10000
	s_cmp_eq_u32 s86, 28
	s_cselect_b32 s83, s11, s81
	s_cselect_b32 s82, s35, s80
	s_cselect_b32 s81, s31, s85
	s_cselect_b32 s80, s79, s84
	s_add_i32 s92, 0, 0x14000
	v_add_u32_e32 v142, s87, v228
	v_add_u32_e32 v158, s92, v228
	ds_read_b128 v[126:129], v142
	ds_read_b128 v[134:137], v142 offset:1024
	ds_read_b128 v[138:141], v142 offset:2048
	ds_read_b128 v[142:145], v142 offset:3072
	ds_read_b128 v[146:149], v158
	ds_read_b128 v[150:153], v158 offset:1024
	ds_read_b128 v[154:157], v158 offset:2048
	ds_read_b128 v[158:161], v158 offset:3072
	v_lshl_add_u64 v[202:203], s[8:9], 0, v[210:211]
	s_add_i32 m0, s61, 0xc000
	ds_read_b128 v[162:165], v233
	ds_read_b128 v[166:169], v233 offset:1024
	ds_read_b128 v[170:173], v233 offset:2048
	ds_read_b128 v[174:177], v233 offset:3072
	ds_read_b128 v[178:181], v233 offset:4096
	ds_read_b128 v[182:185], v233 offset:5120
	ds_read_b128 v[186:189], v233 offset:6144
	ds_read_b128 v[190:193], v233 offset:7168
	global_load_lds_dwordx4 v[202:203], off
	v_lshl_add_u64 v[202:203], s[8:9], 0, v[208:209]
	s_add_i32 m0, s61, 0xe000
	s_nop 0
	global_load_lds_dwordx4 v[202:203], off
	s_waitcnt vmcnt(8)
	s_waitcnt lgkmcnt(0)
	s_barrier
	s_setprio 1
	s_waitcnt lgkmcnt(0)
	v_mfma_f32_16x16x32_bf16 v[130:133], v[126:129], v[162:165], v[130:133]
	v_mfma_f32_16x16x32_bf16 v[122:125], v[138:141], v[162:165], v[122:125]
	v_mfma_f32_16x16x32_bf16 v[106:109], v[138:141], v[170:173], v[106:109]
	v_mfma_f32_16x16x32_bf16 v[110:113], v[126:129], v[170:173], v[110:113]
	v_mfma_f32_16x16x32_bf16 v[94:97], v[126:129], v[178:181], v[94:97]
	v_mfma_f32_16x16x32_bf16 v[90:93], v[138:141], v[178:181], v[90:93]
	v_mfma_f32_16x16x32_bf16 v[74:77], v[138:141], v[186:189], v[74:77]
	v_mfma_f32_16x16x32_bf16 v[78:81], v[126:129], v[186:189], v[78:81]
	v_mfma_f32_16x16x32_bf16 v[130:133], v[134:137], v[166:169], v[130:133]
	v_mfma_f32_16x16x32_bf16 v[122:125], v[142:145], v[166:169], v[122:125]
	v_mfma_f32_16x16x32_bf16 v[106:109], v[142:145], v[174:177], v[106:109]
	v_mfma_f32_16x16x32_bf16 v[110:113], v[134:137], v[174:177], v[110:113]
	v_mfma_f32_16x16x32_bf16 v[94:97], v[134:137], v[182:185], v[94:97]
	v_mfma_f32_16x16x32_bf16 v[90:93], v[142:145], v[182:185], v[90:93]
	v_mfma_f32_16x16x32_bf16 v[74:77], v[142:145], v[190:193], v[74:77]
	v_mfma_f32_16x16x32_bf16 v[78:81], v[134:137], v[190:193], v[78:81]
	s_setprio 0
	s_setprio 1
	v_mfma_f32_16x16x32_bf16 v[118:121], v[146:149], v[162:165], v[118:121]
	v_mfma_f32_16x16x32_bf16 v[114:117], v[154:157], v[162:165], v[114:117]
	v_mfma_f32_16x16x32_bf16 v[98:101], v[154:157], v[170:173], v[98:101]
	v_mfma_f32_16x16x32_bf16 v[102:105], v[146:149], v[170:173], v[102:105]
	v_mfma_f32_16x16x32_bf16 v[86:89], v[146:149], v[178:181], v[86:89]
	v_mfma_f32_16x16x32_bf16 v[82:85], v[154:157], v[178:181], v[82:85]
	v_mfma_f32_16x16x32_bf16 v[66:69], v[154:157], v[186:189], v[66:69]
	v_mfma_f32_16x16x32_bf16 v[70:73], v[146:149], v[186:189], v[70:73]
	v_mfma_f32_16x16x32_bf16 v[118:121], v[150:153], v[166:169], v[118:121]
	v_mfma_f32_16x16x32_bf16 v[114:117], v[158:161], v[166:169], v[114:117]
	v_mfma_f32_16x16x32_bf16 v[98:101], v[158:161], v[174:177], v[98:101]
	v_mfma_f32_16x16x32_bf16 v[102:105], v[150:153], v[174:177], v[102:105]
	v_mfma_f32_16x16x32_bf16 v[86:89], v[150:153], v[182:185], v[86:89]
	v_mfma_f32_16x16x32_bf16 v[82:85], v[158:161], v[182:185], v[82:85]
	v_mfma_f32_16x16x32_bf16 v[66:69], v[158:161], v[190:193], v[66:69]
	v_mfma_f32_16x16x32_bf16 v[70:73], v[150:153], v[190:193], v[70:73]
	s_setprio 0
	s_barrier
	s_add_i32 s87, s87, s95
	v_lshl_add_u64 v[202:203], s[80:81], 0, v[194:195]
	s_mov_b32 m0, s87
	ds_read_b128 v[162:165], v233 offset:16384
	ds_read_b128 v[166:169], v233 offset:17408
	ds_read_b128 v[170:173], v233 offset:18432
	ds_read_b128 v[174:177], v233 offset:19456
	ds_read_b128 v[178:181], v233 offset:20480
	ds_read_b128 v[182:185], v233 offset:21504
	ds_read_b128 v[186:189], v233 offset:22528
	ds_read_b128 v[190:193], v233 offset:23552
	global_load_lds_dwordx4 v[202:203], off
	s_add_i32 m0, s87, 0x2000
	s_add_u32 vcc_lo, s80, 0x80000
	v_lshl_add_u64 v[204:205], s[80:81], 0, v[196:197]
	s_addc_u32 vcc_hi, s81, 0
	s_add_i32 s87, s92, s95
	global_load_lds_dwordx4 v[204:205], off
	v_lshl_add_u64 v[206:207], vcc, 0, v[194:195]
	s_mov_b32 m0, s87
	v_lshl_add_u64 v[214:215], s[82:83], 0, v[196:197]
	global_load_lds_dwordx4 v[206:207], off
	v_lshl_add_u64 v[206:207], vcc, 0, v[196:197]
	s_add_i32 m0, s87, 0x2000
	s_nop 0
	global_load_lds_dwordx4 v[206:207], off
	v_lshl_add_u64 v[206:207], s[82:83], 0, v[194:195]
	s_mov_b32 m0, s61
	s_nop 0
	global_load_lds_dwordx4 v[206:207], off
	s_mov_b32 m0, s44
	s_nop 0
	global_load_lds_dwordx4 v[214:215], off
	s_waitcnt vmcnt(8)
	s_waitcnt lgkmcnt(0)
	s_barrier
	s_setprio 1
	s_waitcnt lgkmcnt(0)
	v_mfma_f32_16x16x32_bf16 v[62:65], v[126:129], v[162:165], v[62:65]
	v_mfma_f32_16x16x32_bf16 v[58:61], v[138:141], v[162:165], v[58:61]
	v_mfma_f32_16x16x32_bf16 v[42:45], v[138:141], v[170:173], v[42:45]
	v_mfma_f32_16x16x32_bf16 v[46:49], v[126:129], v[170:173], v[46:49]
	v_mfma_f32_16x16x32_bf16 v[30:33], v[126:129], v[178:181], v[30:33]
	v_mfma_f32_16x16x32_bf16 v[26:29], v[138:141], v[178:181], v[26:29]
	v_mfma_f32_16x16x32_bf16 v[10:13], v[138:141], v[186:189], v[10:13]
	v_mfma_f32_16x16x32_bf16 v[14:17], v[126:129], v[186:189], v[14:17]
	v_mfma_f32_16x16x32_bf16 v[62:65], v[134:137], v[166:169], v[62:65]
	v_mfma_f32_16x16x32_bf16 v[58:61], v[142:145], v[166:169], v[58:61]
	v_mfma_f32_16x16x32_bf16 v[42:45], v[142:145], v[174:177], v[42:45]
	v_mfma_f32_16x16x32_bf16 v[46:49], v[134:137], v[174:177], v[46:49]
	v_mfma_f32_16x16x32_bf16 v[30:33], v[134:137], v[182:185], v[30:33]
	v_mfma_f32_16x16x32_bf16 v[26:29], v[142:145], v[182:185], v[26:29]
	v_mfma_f32_16x16x32_bf16 v[10:13], v[142:145], v[190:193], v[10:13]
	v_mfma_f32_16x16x32_bf16 v[14:17], v[134:137], v[190:193], v[14:17]
	s_setprio 0
	s_setprio 1
	v_mfma_f32_16x16x32_bf16 v[54:57], v[146:149], v[162:165], v[54:57]
	v_mfma_f32_16x16x32_bf16 v[50:53], v[154:157], v[162:165], v[50:53]
	v_mfma_f32_16x16x32_bf16 v[34:37], v[154:157], v[170:173], v[34:37]
	v_mfma_f32_16x16x32_bf16 v[38:41], v[146:149], v[170:173], v[38:41]
	v_mfma_f32_16x16x32_bf16 v[22:25], v[146:149], v[178:181], v[22:25]
	v_mfma_f32_16x16x32_bf16 v[18:21], v[154:157], v[178:181], v[18:21]
	v_mfma_f32_16x16x32_bf16 v[2:5], v[154:157], v[186:189], v[2:5]
	v_mfma_f32_16x16x32_bf16 v[6:9], v[146:149], v[186:189], v[6:9]
	v_mfma_f32_16x16x32_bf16 v[54:57], v[150:153], v[166:169], v[54:57]
	v_mfma_f32_16x16x32_bf16 v[50:53], v[158:161], v[166:169], v[50:53]
	v_mfma_f32_16x16x32_bf16 v[34:37], v[158:161], v[174:177], v[34:37]
	v_mfma_f32_16x16x32_bf16 v[38:41], v[150:153], v[174:177], v[38:41]
	v_mfma_f32_16x16x32_bf16 v[22:25], v[150:153], v[182:185], v[22:25]
	v_mfma_f32_16x16x32_bf16 v[18:21], v[158:161], v[182:185], v[18:21]
	v_mfma_f32_16x16x32_bf16 v[2:5], v[158:161], v[190:193], v[2:5]
	v_mfma_f32_16x16x32_bf16 v[6:9], v[150:153], v[190:193], v[6:9]
	s_setprio 0
	s_barrier
	s_add_i32 s87, 0, 0x18000
	s_add_i32 s92, 0, 0x1c000
	v_add_u32_e32 v142, s87, v228
	v_add_u32_e32 v158, s92, v228
	ds_read_b128 v[126:129], v142
	ds_read_b128 v[134:137], v142 offset:1024
	ds_read_b128 v[138:141], v142 offset:2048
	ds_read_b128 v[142:145], v142 offset:3072
	ds_read_b128 v[146:149], v158
	ds_read_b128 v[150:153], v158 offset:1024
	ds_read_b128 v[154:157], v158 offset:2048
	ds_read_b128 v[158:161], v158 offset:3072
	s_add_u32 s82, s82, 0x80000
	s_addc_u32 s83, s83, 0
	s_mov_b32 m0, s45
	v_lshl_add_u64 v[216:217], s[82:83], 0, v[194:195]
	ds_read_b128 v[162:165], v233 offset:32768
	ds_read_b128 v[166:169], v233 offset:33792
	ds_read_b128 v[170:173], v233 offset:34816
	ds_read_b128 v[174:177], v233 offset:35840
	ds_read_b128 v[178:181], v233 offset:36864
	ds_read_b128 v[182:185], v233 offset:37888
	ds_read_b128 v[186:189], v233 offset:38912
	ds_read_b128 v[190:193], v233 offset:39936
	global_load_lds_dwordx4 v[216:217], off
	v_lshl_add_u64 v[216:217], s[82:83], 0, v[196:197]
	s_mov_b32 m0, s88
	s_nop 0
	global_load_lds_dwordx4 v[216:217], off
	s_waitcnt vmcnt(8)
	s_waitcnt lgkmcnt(0)
	s_barrier
	s_setprio 1
	s_waitcnt lgkmcnt(0)
	v_mfma_f32_16x16x32_bf16 v[130:133], v[126:129], v[162:165], v[130:133]
	v_mfma_f32_16x16x32_bf16 v[122:125], v[138:141], v[162:165], v[122:125]
	v_mfma_f32_16x16x32_bf16 v[106:109], v[138:141], v[170:173], v[106:109]
	v_mfma_f32_16x16x32_bf16 v[110:113], v[126:129], v[170:173], v[110:113]
	v_mfma_f32_16x16x32_bf16 v[94:97], v[126:129], v[178:181], v[94:97]
	v_mfma_f32_16x16x32_bf16 v[90:93], v[138:141], v[178:181], v[90:93]
	v_mfma_f32_16x16x32_bf16 v[74:77], v[138:141], v[186:189], v[74:77]
	v_mfma_f32_16x16x32_bf16 v[78:81], v[126:129], v[186:189], v[78:81]
	v_mfma_f32_16x16x32_bf16 v[130:133], v[134:137], v[166:169], v[130:133]
	v_mfma_f32_16x16x32_bf16 v[122:125], v[142:145], v[166:169], v[122:125]
	v_mfma_f32_16x16x32_bf16 v[106:109], v[142:145], v[174:177], v[106:109]
	v_mfma_f32_16x16x32_bf16 v[110:113], v[134:137], v[174:177], v[110:113]
	v_mfma_f32_16x16x32_bf16 v[94:97], v[134:137], v[182:185], v[94:97]
	v_mfma_f32_16x16x32_bf16 v[90:93], v[142:145], v[182:185], v[90:93]
	v_mfma_f32_16x16x32_bf16 v[74:77], v[142:145], v[190:193], v[74:77]
	v_mfma_f32_16x16x32_bf16 v[78:81], v[134:137], v[190:193], v[78:81]
	s_setprio 0
	s_setprio 1
	v_mfma_f32_16x16x32_bf16 v[118:121], v[146:149], v[162:165], v[118:121]
	v_mfma_f32_16x16x32_bf16 v[114:117], v[154:157], v[162:165], v[114:117]
	v_mfma_f32_16x16x32_bf16 v[98:101], v[154:157], v[170:173], v[98:101]
	v_mfma_f32_16x16x32_bf16 v[102:105], v[146:149], v[170:173], v[102:105]
	v_mfma_f32_16x16x32_bf16 v[86:89], v[146:149], v[178:181], v[86:89]
	v_mfma_f32_16x16x32_bf16 v[82:85], v[154:157], v[178:181], v[82:85]
	v_mfma_f32_16x16x32_bf16 v[66:69], v[154:157], v[186:189], v[66:69]
	v_mfma_f32_16x16x32_bf16 v[70:73], v[146:149], v[186:189], v[70:73]
	v_mfma_f32_16x16x32_bf16 v[118:121], v[150:153], v[166:169], v[118:121]
	v_mfma_f32_16x16x32_bf16 v[114:117], v[158:161], v[166:169], v[114:117]
	v_mfma_f32_16x16x32_bf16 v[98:101], v[158:161], v[174:177], v[98:101]
	v_mfma_f32_16x16x32_bf16 v[102:105], v[150:153], v[174:177], v[102:105]
	v_mfma_f32_16x16x32_bf16 v[86:89], v[150:153], v[182:185], v[86:89]
	v_mfma_f32_16x16x32_bf16 v[82:85], v[158:161], v[182:185], v[82:85]
	v_mfma_f32_16x16x32_bf16 v[66:69], v[158:161], v[190:193], v[66:69]
	v_mfma_f32_16x16x32_bf16 v[70:73], v[150:153], v[190:193], v[70:73]
	s_setprio 0
	s_barrier
	s_add_i32 s82, s87, s95
	v_lshl_add_u64 v[202:203], v[202:203], 0, s[54:55]
	s_mov_b32 m0, s82
	ds_read_b128 v[162:165], v233 offset:49152
	ds_read_b128 v[166:169], v233 offset:50176
	ds_read_b128 v[170:173], v233 offset:51200
	ds_read_b128 v[174:177], v233 offset:52224
	ds_read_b128 v[178:181], v233 offset:53248
	ds_read_b128 v[182:185], v233 offset:54272
	ds_read_b128 v[186:189], v233 offset:55296
	ds_read_b128 v[190:193], v233 offset:56320
	global_load_lds_dwordx4 v[202:203], off
	s_add_i32 m0, s82, 0x2000
	s_add_u32 s80, s80, 0x80080
	v_lshl_add_u64 v[202:203], v[204:205], 0, s[54:55]
	s_addc_u32 s81, s81, 0
	s_add_i32 s82, s92, s95
	global_load_lds_dwordx4 v[202:203], off
	v_lshl_add_u64 v[202:203], s[80:81], 0, v[194:195]
	s_mov_b32 m0, s82
	s_nop 0
	global_load_lds_dwordx4 v[202:203], off
	v_lshl_add_u64 v[202:203], s[80:81], 0, v[196:197]
	s_add_i32 m0, s82, 0x2000
	s_nop 0
	global_load_lds_dwordx4 v[202:203], off
	v_lshl_add_u64 v[202:203], v[206:207], 0, s[54:55]
	s_mov_b32 m0, s48
	s_nop 0
	global_load_lds_dwordx4 v[202:203], off
	v_lshl_add_u64 v[202:203], v[214:215], 0, s[54:55]
	s_mov_b32 m0, s49
	s_nop 0
	global_load_lds_dwordx4 v[202:203], off
	s_waitcnt vmcnt(8)
	s_waitcnt lgkmcnt(0)
	s_barrier
	s_setprio 1
	s_waitcnt lgkmcnt(0)
	v_mfma_f32_16x16x32_bf16 v[62:65], v[126:129], v[162:165], v[62:65]
	v_mfma_f32_16x16x32_bf16 v[58:61], v[138:141], v[162:165], v[58:61]
	v_mfma_f32_16x16x32_bf16 v[42:45], v[138:141], v[170:173], v[42:45]
	v_mfma_f32_16x16x32_bf16 v[46:49], v[126:129], v[170:173], v[46:49]
	v_mfma_f32_16x16x32_bf16 v[30:33], v[126:129], v[178:181], v[30:33]
	v_mfma_f32_16x16x32_bf16 v[26:29], v[138:141], v[178:181], v[26:29]
	v_mfma_f32_16x16x32_bf16 v[10:13], v[138:141], v[186:189], v[10:13]
	v_mfma_f32_16x16x32_bf16 v[14:17], v[126:129], v[186:189], v[14:17]
	v_mfma_f32_16x16x32_bf16 v[62:65], v[134:137], v[166:169], v[62:65]
	v_mfma_f32_16x16x32_bf16 v[58:61], v[142:145], v[166:169], v[58:61]
	v_mfma_f32_16x16x32_bf16 v[42:45], v[142:145], v[174:177], v[42:45]
	v_mfma_f32_16x16x32_bf16 v[46:49], v[134:137], v[174:177], v[46:49]
	v_mfma_f32_16x16x32_bf16 v[30:33], v[134:137], v[182:185], v[30:33]
	v_mfma_f32_16x16x32_bf16 v[26:29], v[142:145], v[182:185], v[26:29]
	v_mfma_f32_16x16x32_bf16 v[10:13], v[142:145], v[190:193], v[10:13]
	v_mfma_f32_16x16x32_bf16 v[14:17], v[134:137], v[190:193], v[14:17]
	s_setprio 0
	s_setprio 1
	v_mfma_f32_16x16x32_bf16 v[54:57], v[146:149], v[162:165], v[54:57]
	v_mfma_f32_16x16x32_bf16 v[50:53], v[154:157], v[162:165], v[50:53]
	v_mfma_f32_16x16x32_bf16 v[34:37], v[154:157], v[170:173], v[34:37]
	v_mfma_f32_16x16x32_bf16 v[38:41], v[146:149], v[170:173], v[38:41]
	v_mfma_f32_16x16x32_bf16 v[22:25], v[146:149], v[178:181], v[22:25]
	v_mfma_f32_16x16x32_bf16 v[18:21], v[154:157], v[178:181], v[18:21]
	v_mfma_f32_16x16x32_bf16 v[2:5], v[154:157], v[186:189], v[2:5]
	v_mfma_f32_16x16x32_bf16 v[6:9], v[146:149], v[186:189], v[6:9]
	v_mfma_f32_16x16x32_bf16 v[54:57], v[150:153], v[166:169], v[54:57]
	v_mfma_f32_16x16x32_bf16 v[50:53], v[158:161], v[166:169], v[50:53]
	v_mfma_f32_16x16x32_bf16 v[34:37], v[158:161], v[174:177], v[34:37]
	v_mfma_f32_16x16x32_bf16 v[38:41], v[150:153], v[174:177], v[38:41]
	v_mfma_f32_16x16x32_bf16 v[22:25], v[150:153], v[182:185], v[22:25]
	v_mfma_f32_16x16x32_bf16 v[18:21], v[158:161], v[182:185], v[18:21]
	v_mfma_f32_16x16x32_bf16 v[2:5], v[158:161], v[190:193], v[2:5]
	v_mfma_f32_16x16x32_bf16 v[6:9], v[150:153], v[190:193], v[6:9]
	s_setprio 0
	s_barrier
	s_add_i32 s86, s86, 2
	s_add_u32 s84, s84, 0x100
	s_addc_u32 s85, s85, 0
	s_add_u32 s8, s8, 0x100
	s_addc_u32 s9, s9, 0
	s_cmp_gt_u32 s86, 29
	s_cbranch_scc0 .LBB0_605
	s_and_b64 vcc, exec, s[28:29]
	s_cbranch_vccz .LBB0_608
	s_barrier

.LBB0_885:
	s_add_u32 s38, s24, s36
	s_addc_u32 s39, s25, s37
	s_add_u32 s38, s38, 0x100
	s_addc_u32 s39, s39, 0
	s_add_u32 s88, s72, s36
	s_addc_u32 s89, s73, s37
	s_add_i32 s92, 0, 0x10000
	s_cmpk_eq_i32 s36, 0xf00
	s_cselect_b32 s79, s29, s39
	s_cselect_b32 s78, s81, s38
	s_cselect_b32 s39, s27, s89
	s_cselect_b32 s38, s86, s88
	s_add_i32 s93, 0, 0x14000
	v_add_u32_e32 v154, s92, v140
	v_add_u32_e32 v170, s93, v140
	ds_read_b128 v[142:145], v154
	ds_read_b128 v[146:149], v154 offset:1024
	ds_read_b128 v[150:153], v154 offset:2048
	ds_read_b128 v[154:157], v154 offset:3072
	ds_read_b128 v[158:161], v170
	ds_read_b128 v[162:165], v170 offset:1024
	ds_read_b128 v[166:169], v170 offset:2048
	ds_read_b128 v[170:173], v170 offset:3072
	v_lshl_add_u64 v[206:207], v[138:139], 0, s[36:37]
	s_add_i32 m0, s21, 0xc000
	ds_read_b128 v[174:177], v141
	ds_read_b128 v[178:181], v141 offset:1024
	ds_read_b128 v[182:185], v141 offset:2048
	ds_read_b128 v[186:189], v141 offset:3072
	ds_read_b128 v[190:193], v141 offset:4096
	ds_read_b128 v[194:197], v141 offset:5120
	ds_read_b128 v[198:201], v141 offset:6144
	ds_read_b128 v[202:205], v141 offset:7168
	global_load_lds_dwordx4 v[206:207], off
	v_lshl_add_u64 v[206:207], v[136:137], 0, s[36:37]
	s_add_i32 m0, s21, 0xe000
	s_nop 0
	global_load_lds_dwordx4 v[206:207], off
	s_waitcnt vmcnt(8)
	s_waitcnt lgkmcnt(0)
	s_barrier
	s_setprio 1
	s_waitcnt lgkmcnt(0)
	v_mfma_f32_16x16x32_bf16 v[126:129], v[142:145], v[174:177], v[126:129]
	v_mfma_f32_16x16x32_bf16 v[122:125], v[150:153], v[174:177], v[122:125]
	v_mfma_f32_16x16x32_bf16 v[106:109], v[150:153], v[182:185], v[106:109]
	v_mfma_f32_16x16x32_bf16 v[110:113], v[142:145], v[182:185], v[110:113]
	v_mfma_f32_16x16x32_bf16 v[98:101], v[142:145], v[190:193], v[98:101]
	v_mfma_f32_16x16x32_bf16 v[90:93], v[150:153], v[190:193], v[90:93]
	v_mfma_f32_16x16x32_bf16 v[74:77], v[150:153], v[198:201], v[74:77]
	v_mfma_f32_16x16x32_bf16 v[82:85], v[142:145], v[198:201], v[82:85]
	v_mfma_f32_16x16x32_bf16 v[126:129], v[146:149], v[178:181], v[126:129]
	v_mfma_f32_16x16x32_bf16 v[122:125], v[154:157], v[178:181], v[122:125]
	v_mfma_f32_16x16x32_bf16 v[106:109], v[154:157], v[186:189], v[106:109]
	v_mfma_f32_16x16x32_bf16 v[110:113], v[146:149], v[186:189], v[110:113]
	v_mfma_f32_16x16x32_bf16 v[98:101], v[146:149], v[194:197], v[98:101]
	v_mfma_f32_16x16x32_bf16 v[90:93], v[154:157], v[194:197], v[90:93]
	v_mfma_f32_16x16x32_bf16 v[74:77], v[154:157], v[202:205], v[74:77]
	v_mfma_f32_16x16x32_bf16 v[82:85], v[146:149], v[202:205], v[82:85]
	s_setprio 0
	s_setprio 1
	v_mfma_f32_16x16x32_bf16 v[118:121], v[158:161], v[174:177], v[118:121]
	v_mfma_f32_16x16x32_bf16 v[114:117], v[166:169], v[174:177], v[114:117]
	v_mfma_f32_16x16x32_bf16 v[94:97], v[166:169], v[182:185], v[94:97]
	v_mfma_f32_16x16x32_bf16 v[102:105], v[158:161], v[182:185], v[102:105]
	v_mfma_f32_16x16x32_bf16 v[86:89], v[158:161], v[190:193], v[86:89]
	v_mfma_f32_16x16x32_bf16 v[78:81], v[166:169], v[190:193], v[78:81]
	v_mfma_f32_16x16x32_bf16 v[66:69], v[166:169], v[198:201], v[66:69]
	v_mfma_f32_16x16x32_bf16 v[70:73], v[158:161], v[198:201], v[70:73]
	v_mfma_f32_16x16x32_bf16 v[118:121], v[162:165], v[178:181], v[118:121]
	v_mfma_f32_16x16x32_bf16 v[114:117], v[170:173], v[178:181], v[114:117]
	v_mfma_f32_16x16x32_bf16 v[94:97], v[170:173], v[186:189], v[94:97]
	v_mfma_f32_16x16x32_bf16 v[102:105], v[162:165], v[186:189], v[102:105]
	v_mfma_f32_16x16x32_bf16 v[86:89], v[162:165], v[194:197], v[86:89]
	v_mfma_f32_16x16x32_bf16 v[78:81], v[170:173], v[194:197], v[78:81]
	v_mfma_f32_16x16x32_bf16 v[66:69], v[170:173], v[202:205], v[66:69]
	v_mfma_f32_16x16x32_bf16 v[70:73], v[162:165], v[202:205], v[70:73]
	s_setprio 0
	s_barrier
	s_add_i32 s88, s92, s48
	v_lshl_add_u64 v[206:207], s[38:39], 0, v[0:1]
	s_mov_b32 m0, s88
	ds_read_b128 v[174:177], v141 offset:16384
	ds_read_b128 v[178:181], v141 offset:17408
	ds_read_b128 v[182:185], v141 offset:18432
	ds_read_b128 v[186:189], v141 offset:19456
	ds_read_b128 v[190:193], v141 offset:20480
	ds_read_b128 v[194:197], v141 offset:21504
	ds_read_b128 v[198:201], v141 offset:22528
	ds_read_b128 v[202:205], v141 offset:23552
	global_load_lds_dwordx4 v[206:207], off
	s_add_i32 m0, s88, 0x2000
	s_add_u32 s88, s38, 0x80000
	v_lshl_add_u64 v[208:209], s[38:39], 0, v[130:131]
	s_addc_u32 s89, s39, 0
	s_add_i32 s92, s93, s48
	global_load_lds_dwordx4 v[208:209], off
	v_lshl_add_u64 v[214:215], s[88:89], 0, v[0:1]
	s_mov_b32 m0, s92
	v_lshl_add_u64 v[216:217], s[78:79], 0, v[130:131]
	global_load_lds_dwordx4 v[214:215], off
	v_lshl_add_u64 v[214:215], s[88:89], 0, v[130:131]
	s_add_i32 m0, s92, 0x2000
	s_nop 0
	global_load_lds_dwordx4 v[214:215], off
	v_lshl_add_u64 v[214:215], s[78:79], 0, v[0:1]
	s_mov_b32 m0, s21
	s_nop 0
	global_load_lds_dwordx4 v[214:215], off
	s_mov_b32 m0, s49
	s_nop 0
	global_load_lds_dwordx4 v[216:217], off
	s_waitcnt vmcnt(8)
	s_waitcnt lgkmcnt(0)
	s_barrier
	s_setprio 1
	s_waitcnt lgkmcnt(0)
	v_mfma_f32_16x16x32_bf16 v[62:65], v[142:145], v[174:177], v[62:65]
	v_mfma_f32_16x16x32_bf16 v[58:61], v[150:153], v[174:177], v[58:61]
	v_mfma_f32_16x16x32_bf16 v[42:45], v[150:153], v[182:185], v[42:45]
	v_mfma_f32_16x16x32_bf16 v[50:53], v[142:145], v[182:185], v[50:53]
	v_mfma_f32_16x16x32_bf16 v[34:37], v[142:145], v[190:193], v[34:37]
	v_mfma_f32_16x16x32_bf16 v[26:29], v[150:153], v[190:193], v[26:29]
	v_mfma_f32_16x16x32_bf16 v[10:13], v[150:153], v[198:201], v[10:13]
	v_mfma_f32_16x16x32_bf16 v[18:21], v[142:145], v[198:201], v[18:21]
	v_mfma_f32_16x16x32_bf16 v[62:65], v[146:149], v[178:181], v[62:65]
	v_mfma_f32_16x16x32_bf16 v[58:61], v[154:157], v[178:181], v[58:61]
	v_mfma_f32_16x16x32_bf16 v[42:45], v[154:157], v[186:189], v[42:45]
	v_mfma_f32_16x16x32_bf16 v[50:53], v[146:149], v[186:189], v[50:53]
	v_mfma_f32_16x16x32_bf16 v[34:37], v[146:149], v[194:197], v[34:37]
	v_mfma_f32_16x16x32_bf16 v[26:29], v[154:157], v[194:197], v[26:29]
	v_mfma_f32_16x16x32_bf16 v[10:13], v[154:157], v[202:205], v[10:13]
	v_mfma_f32_16x16x32_bf16 v[18:21], v[146:149], v[202:205], v[18:21]
	s_setprio 0
	s_setprio 1
	v_mfma_f32_16x16x32_bf16 v[54:57], v[158:161], v[174:177], v[54:57]
	v_mfma_f32_16x16x32_bf16 v[46:49], v[166:169], v[174:177], v[46:49]
	v_mfma_f32_16x16x32_bf16 v[30:33], v[166:169], v[182:185], v[30:33]
	v_mfma_f32_16x16x32_bf16 v[38:41], v[158:161], v[182:185], v[38:41]
	v_mfma_f32_16x16x32_bf16 v[22:25], v[158:161], v[190:193], v[22:25]
	v_mfma_f32_16x16x32_bf16 v[14:17], v[166:169], v[190:193], v[14:17]
	v_mfma_f32_16x16x32_bf16 v[2:5], v[166:169], v[198:201], v[2:5]
	v_mfma_f32_16x16x32_bf16 v[6:9], v[158:161], v[198:201], v[6:9]
	v_mfma_f32_16x16x32_bf16 v[54:57], v[162:165], v[178:181], v[54:57]
	v_mfma_f32_16x16x32_bf16 v[46:49], v[170:173], v[178:181], v[46:49]
	v_mfma_f32_16x16x32_bf16 v[30:33], v[170:173], v[186:189], v[30:33]
	v_mfma_f32_16x16x32_bf16 v[38:41], v[162:165], v[186:189], v[38:41]
	v_mfma_f32_16x16x32_bf16 v[22:25], v[162:165], v[194:197], v[22:25]
	v_mfma_f32_16x16x32_bf16 v[14:17], v[170:173], v[194:197], v[14:17]
	v_mfma_f32_16x16x32_bf16 v[2:5], v[170:173], v[202:205], v[2:5]
	v_mfma_f32_16x16x32_bf16 v[6:9], v[162:165], v[202:205], v[6:9]
	s_setprio 0
	s_barrier
	s_add_i32 s88, 0, 0x18000
	s_add_i32 s89, 0, 0x1c000
	v_add_u32_e32 v154, s88, v140
	v_add_u32_e32 v170, s89, v140
	ds_read_b128 v[142:145], v154
	ds_read_b128 v[146:149], v154 offset:1024
	ds_read_b128 v[150:153], v154 offset:2048
	ds_read_b128 v[154:157], v154 offset:3072
	ds_read_b128 v[158:161], v170
	ds_read_b128 v[162:165], v170 offset:1024
	ds_read_b128 v[166:169], v170 offset:2048
	ds_read_b128 v[170:173], v170 offset:3072
	s_add_u32 s78, s78, 0x80000
	s_addc_u32 s79, s79, 0
	s_mov_b32 m0, s61
	v_lshl_add_u64 v[218:219], s[78:79], 0, v[0:1]
	ds_read_b128 v[174:177], v141 offset:32768
	ds_read_b128 v[178:181], v141 offset:33792
	ds_read_b128 v[182:185], v141 offset:34816
	ds_read_b128 v[186:189], v141 offset:35840
	ds_read_b128 v[190:193], v141 offset:36864
	ds_read_b128 v[194:197], v141 offset:37888
	ds_read_b128 v[198:201], v141 offset:38912
	ds_read_b128 v[202:205], v141 offset:39936
	global_load_lds_dwordx4 v[218:219], off
	v_lshl_add_u64 v[218:219], s[78:79], 0, v[130:131]
	s_mov_b32 m0, s65
	s_nop 0
	global_load_lds_dwordx4 v[218:219], off
	s_waitcnt vmcnt(8)
	s_waitcnt lgkmcnt(0)
	s_barrier
	s_setprio 1
	s_waitcnt lgkmcnt(0)
	v_mfma_f32_16x16x32_bf16 v[126:129], v[142:145], v[174:177], v[126:129]
	v_mfma_f32_16x16x32_bf16 v[122:125], v[150:153], v[174:177], v[122:125]
	v_mfma_f32_16x16x32_bf16 v[106:109], v[150:153], v[182:185], v[106:109]
	v_mfma_f32_16x16x32_bf16 v[110:113], v[142:145], v[182:185], v[110:113]
	v_mfma_f32_16x16x32_bf16 v[98:101], v[142:145], v[190:193], v[98:101]
	v_mfma_f32_16x16x32_bf16 v[90:93], v[150:153], v[190:193], v[90:93]
	v_mfma_f32_16x16x32_bf16 v[74:77], v[150:153], v[198:201], v[74:77]
	v_mfma_f32_16x16x32_bf16 v[82:85], v[142:145], v[198:201], v[82:85]
	v_mfma_f32_16x16x32_bf16 v[126:129], v[146:149], v[178:181], v[126:129]
	v_mfma_f32_16x16x32_bf16 v[122:125], v[154:157], v[178:181], v[122:125]
	v_mfma_f32_16x16x32_bf16 v[106:109], v[154:157], v[186:189], v[106:109]
	v_mfma_f32_16x16x32_bf16 v[110:113], v[146:149], v[186:189], v[110:113]
	v_mfma_f32_16x16x32_bf16 v[98:101], v[146:149], v[194:197], v[98:101]
	v_mfma_f32_16x16x32_bf16 v[90:93], v[154:157], v[194:197], v[90:93]
	v_mfma_f32_16x16x32_bf16 v[74:77], v[154:157], v[202:205], v[74:77]
	v_mfma_f32_16x16x32_bf16 v[82:85], v[146:149], v[202:205], v[82:85]
	s_setprio 0
	s_setprio 1
	v_mfma_f32_16x16x32_bf16 v[118:121], v[158:161], v[174:177], v[118:121]
	v_mfma_f32_16x16x32_bf16 v[114:117], v[166:169], v[174:177], v[114:117]
	v_mfma_f32_16x16x32_bf16 v[94:97], v[166:169], v[182:185], v[94:97]
	v_mfma_f32_16x16x32_bf16 v[102:105], v[158:161], v[182:185], v[102:105]
	v_mfma_f32_16x16x32_bf16 v[86:89], v[158:161], v[190:193], v[86:89]
	v_mfma_f32_16x16x32_bf16 v[78:81], v[166:169], v[190:193], v[78:81]
	v_mfma_f32_16x16x32_bf16 v[66:69], v[166:169], v[198:201], v[66:69]
	v_mfma_f32_16x16x32_bf16 v[70:73], v[158:161], v[198:201], v[70:73]
	v_mfma_f32_16x16x32_bf16 v[118:121], v[162:165], v[178:181], v[118:121]
	v_mfma_f32_16x16x32_bf16 v[114:117], v[170:173], v[178:181], v[114:117]
	v_mfma_f32_16x16x32_bf16 v[94:97], v[170:173], v[186:189], v[94:97]
	v_mfma_f32_16x16x32_bf16 v[102:105], v[162:165], v[186:189], v[102:105]
	v_mfma_f32_16x16x32_bf16 v[86:89], v[162:165], v[194:197], v[86:89]
	v_mfma_f32_16x16x32_bf16 v[78:81], v[170:173], v[194:197], v[78:81]
	v_mfma_f32_16x16x32_bf16 v[66:69], v[170:173], v[202:205], v[66:69]
	v_mfma_f32_16x16x32_bf16 v[70:73], v[162:165], v[202:205], v[70:73]
	s_setprio 0
	s_barrier
	s_add_i32 s78, s88, s48
	v_lshl_add_u64 v[206:207], v[206:207], 0, s[54:55]
	s_mov_b32 m0, s78
	ds_read_b128 v[174:177], v141 offset:49152
	ds_read_b128 v[178:181], v141 offset:50176
	ds_read_b128 v[182:185], v141 offset:51200
	ds_read_b128 v[186:189], v141 offset:52224
	ds_read_b128 v[190:193], v141 offset:53248
	ds_read_b128 v[194:197], v141 offset:54272
	ds_read_b128 v[198:201], v141 offset:55296
	ds_read_b128 v[202:205], v141 offset:56320
	global_load_lds_dwordx4 v[206:207], off
	s_add_i32 m0, s78, 0x2000
	s_add_u32 s38, s38, 0x80080
	v_lshl_add_u64 v[206:207], v[208:209], 0, s[54:55]
	s_addc_u32 s39, s39, 0
	s_add_i32 s78, s89, s48
	global_load_lds_dwordx4 v[206:207], off
	v_lshl_add_u64 v[206:207], s[38:39], 0, v[0:1]
	s_mov_b32 m0, s78
	s_nop 0
	global_load_lds_dwordx4 v[206:207], off
	v_lshl_add_u64 v[206:207], s[38:39], 0, v[130:131]
	s_add_i32 m0, s78, 0x2000
	s_nop 0
	global_load_lds_dwordx4 v[206:207], off
	v_lshl_add_u64 v[206:207], v[214:215], 0, s[54:55]
	s_mov_b32 m0, s68
	s_nop 0
	global_load_lds_dwordx4 v[206:207], off
	v_lshl_add_u64 v[206:207], v[216:217], 0, s[54:55]
	s_mov_b32 m0, s69
	s_nop 0
	global_load_lds_dwordx4 v[206:207], off
	s_waitcnt vmcnt(8)
	s_waitcnt lgkmcnt(0)
	s_barrier
	s_setprio 1
	s_waitcnt lgkmcnt(0)
	v_mfma_f32_16x16x32_bf16 v[62:65], v[142:145], v[174:177], v[62:65]
	v_mfma_f32_16x16x32_bf16 v[58:61], v[150:153], v[174:177], v[58:61]
	v_mfma_f32_16x16x32_bf16 v[42:45], v[150:153], v[182:185], v[42:45]
	v_mfma_f32_16x16x32_bf16 v[50:53], v[142:145], v[182:185], v[50:53]
	v_mfma_f32_16x16x32_bf16 v[34:37], v[142:145], v[190:193], v[34:37]
	v_mfma_f32_16x16x32_bf16 v[26:29], v[150:153], v[190:193], v[26:29]
	v_mfma_f32_16x16x32_bf16 v[10:13], v[150:153], v[198:201], v[10:13]
	v_mfma_f32_16x16x32_bf16 v[18:21], v[142:145], v[198:201], v[18:21]
	v_mfma_f32_16x16x32_bf16 v[62:65], v[146:149], v[178:181], v[62:65]
	v_mfma_f32_16x16x32_bf16 v[58:61], v[154:157], v[178:181], v[58:61]
	v_mfma_f32_16x16x32_bf16 v[42:45], v[154:157], v[186:189], v[42:45]
	v_mfma_f32_16x16x32_bf16 v[50:53], v[146:149], v[186:189], v[50:53]
	v_mfma_f32_16x16x32_bf16 v[34:37], v[146:149], v[194:197], v[34:37]
	v_mfma_f32_16x16x32_bf16 v[26:29], v[154:157], v[194:197], v[26:29]
	v_mfma_f32_16x16x32_bf16 v[10:13], v[154:157], v[202:205], v[10:13]
	v_mfma_f32_16x16x32_bf16 v[18:21], v[146:149], v[202:205], v[18:21]
	s_setprio 0
	s_setprio 1
	v_mfma_f32_16x16x32_bf16 v[54:57], v[158:161], v[174:177], v[54:57]
	v_mfma_f32_16x16x32_bf16 v[46:49], v[166:169], v[174:177], v[46:49]
	v_mfma_f32_16x16x32_bf16 v[30:33], v[166:169], v[182:185], v[30:33]
	v_mfma_f32_16x16x32_bf16 v[38:41], v[158:161], v[182:185], v[38:41]
	v_mfma_f32_16x16x32_bf16 v[22:25], v[158:161], v[190:193], v[22:25]
	v_mfma_f32_16x16x32_bf16 v[14:17], v[166:169], v[190:193], v[14:17]
	v_mfma_f32_16x16x32_bf16 v[2:5], v[166:169], v[198:201], v[2:5]
	v_mfma_f32_16x16x32_bf16 v[6:9], v[158:161], v[198:201], v[6:9]
	v_mfma_f32_16x16x32_bf16 v[54:57], v[162:165], v[178:181], v[54:57]
	v_mfma_f32_16x16x32_bf16 v[46:49], v[170:173], v[178:181], v[46:49]
	v_mfma_f32_16x16x32_bf16 v[30:33], v[170:173], v[186:189], v[30:33]
	v_mfma_f32_16x16x32_bf16 v[38:41], v[162:165], v[186:189], v[38:41]
	v_mfma_f32_16x16x32_bf16 v[22:25], v[162:165], v[194:197], v[22:25]
	v_mfma_f32_16x16x32_bf16 v[14:17], v[170:173], v[194:197], v[14:17]
	v_mfma_f32_16x16x32_bf16 v[2:5], v[170:173], v[202:205], v[2:5]
	v_mfma_f32_16x16x32_bf16 v[6:9], v[162:165], v[202:205], v[6:9]
	s_setprio 0
	s_barrier
	s_add_i32 s87, s87, 2
	s_add_u32 s36, s36, 0x100
	s_addc_u32 s37, s37, 0
	s_cmp_gt_u32 s87, 29
	s_cbranch_scc0 .LBB0_885
	s_add_u32 s36, s72, 0xffffff00
	s_addc_u32 s37, s73, -1
	s_andn2_b64 vcc, exec, s[6:7]
	s_cbranch_vccnz .LBB0_888
	v_mov_b32_e32 v2, 0
	s_mov_b32 s18, s26
	s_mov_b32 s20, s28
	s_mov_b64 s[24:25], s[34:35]
	s_mov_b32 s70, s71
	v_mov_b32_e32 v3, v2
	v_mov_b32_e32 v4, v2
	v_mov_b32_e32 v5, v2
	v_mov_b32_e32 v6, v2
	v_mov_b32_e32 v7, v2
	v_mov_b32_e32 v8, v2
	v_mov_b32_e32 v9, v2
	v_mov_b32_e32 v14, v2
	v_mov_b32_e32 v15, v2
	v_mov_b32_e32 v16, v2
	v_mov_b32_e32 v17, v2
	v_mov_b32_e32 v22, v2
	v_mov_b32_e32 v23, v2
	v_mov_b32_e32 v24, v2
	v_mov_b32_e32 v25, v2
	v_mov_b32_e32 v30, v2
	v_mov_b32_e32 v31, v2
	v_mov_b32_e32 v32, v2
	v_mov_b32_e32 v33, v2
	v_mov_b32_e32 v38, v2
	v_mov_b32_e32 v39, v2
	v_mov_b32_e32 v40, v2
	v_mov_b32_e32 v41, v2
	v_mov_b32_e32 v46, v2
	v_mov_b32_e32 v47, v2
	v_mov_b32_e32 v48, v2
	v_mov_b32_e32 v49, v2
	v_mov_b32_e32 v54, v2
	v_mov_b32_e32 v55, v2
	v_mov_b32_e32 v56, v2
	v_mov_b32_e32 v57, v2
	v_mov_b32_e32 v10, v2
	v_mov_b32_e32 v11, v2
	v_mov_b32_e32 v12, v2
	v_mov_b32_e32 v13, v2
	v_mov_b32_e32 v18, v2
	v_mov_b32_e32 v19, v2
	v_mov_b32_e32 v20, v2
	v_mov_b32_e32 v21, v2
	v_mov_b32_e32 v26, v2
	v_mov_b32_e32 v27, v2
	v_mov_b32_e32 v28, v2
	v_mov_b32_e32 v29, v2
	v_mov_b32_e32 v34, v2
	v_mov_b32_e32 v35, v2
	v_mov_b32_e32 v36, v2
	v_mov_b32_e32 v37, v2
	v_mov_b32_e32 v42, v2
	v_mov_b32_e32 v43, v2
	v_mov_b32_e32 v44, v2
	v_mov_b32_e32 v45, v2
	v_mov_b32_e32 v50, v2
	v_mov_b32_e32 v51, v2
	v_mov_b32_e32 v52, v2
	v_mov_b32_e32 v53, v2
	v_mov_b32_e32 v58, v2
	v_mov_b32_e32 v59, v2
	v_mov_b32_e32 v60, v2
	v_mov_b32_e32 v61, v2
	v_mov_b32_e32 v62, v2
	v_mov_b32_e32 v63, v2
	v_mov_b32_e32 v64, v2
	v_mov_b32_e32 v65, v2
	v_mov_b32_e32 v66, v2
	v_mov_b32_e32 v67, v2
	v_mov_b32_e32 v68, v2
	v_mov_b32_e32 v69, v2
	v_mov_b32_e32 v70, v2
	v_mov_b32_e32 v71, v2
	v_mov_b32_e32 v72, v2
	v_mov_b32_e32 v73, v2
	v_mov_b32_e32 v78, v2
	v_mov_b32_e32 v79, v2
	v_mov_b32_e32 v80, v2
	v_mov_b32_e32 v81, v2
	v_mov_b32_e32 v86, v2
	v_mov_b32_e32 v87, v2
	v_mov_b32_e32 v88, v2
	v_mov_b32_e32 v89, v2
	v_mov_b32_e32 v94, v2
	v_mov_b32_e32 v95, v2
	v_mov_b32_e32 v96, v2
	v_mov_b32_e32 v97, v2
	v_mov_b32_e32 v102, v2
	v_mov_b32_e32 v103, v2
	v_mov_b32_e32 v104, v2
	v_mov_b32_e32 v105, v2
	v_mov_b32_e32 v114, v2
	v_mov_b32_e32 v115, v2
	v_mov_b32_e32 v116, v2
	v_mov_b32_e32 v117, v2
	v_mov_b32_e32 v118, v2
	v_mov_b32_e32 v119, v2
	v_mov_b32_e32 v120, v2
	v_mov_b32_e32 v121, v2
	v_mov_b32_e32 v74, v2
	v_mov_b32_e32 v75, v2
	v_mov_b32_e32 v76, v2
	v_mov_b32_e32 v77, v2
	v_mov_b32_e32 v82, v2
	v_mov_b32_e32 v83, v2
	v_mov_b32_e32 v84, v2
	v_mov_b32_e32 v85, v2
	v_mov_b32_e32 v90, v2
	v_mov_b32_e32 v91, v2
	v_mov_b32_e32 v92, v2
	v_mov_b32_e32 v93, v2
	v_mov_b32_e32 v98, v2
	v_mov_b32_e32 v99, v2
	v_mov_b32_e32 v100, v2
	v_mov_b32_e32 v101, v2
	v_mov_b32_e32 v106, v2
	v_mov_b32_e32 v107, v2
	v_mov_b32_e32 v108, v2
	v_mov_b32_e32 v109, v2
	v_mov_b32_e32 v110, v2
	v_mov_b32_e32 v111, v2
	v_mov_b32_e32 v112, v2
	v_mov_b32_e32 v113, v2
	v_mov_b32_e32 v122, v2
	v_mov_b32_e32 v123, v2
	v_mov_b32_e32 v124, v2
	v_mov_b32_e32 v125, v2
	v_mov_b32_e32 v126, v2
	v_mov_b32_e32 v127, v2
	v_mov_b32_e32 v128, v2
	v_mov_b32_e32 v129, v2
	s_andn2_b64 vcc, exec, s[4:5]
	s_cbranch_vccnz .LBB0_889
	s_branch .LBB0_892

.LBB0_947:
	s_add_u32 s78, s26, s38
	s_addc_u32 s79, s27, s39
	s_add_u32 s78, s78, 0x100
	s_addc_u32 s79, s79, 0
	s_add_u32 s92, s72, s38
	s_addc_u32 s93, s73, s39
	s_add_i32 s94, 0, 0x10000
	s_cmpk_eq_i32 s38, 0xf00
	s_cselect_b32 s81, s31, s79
	s_cselect_b32 s80, s87, s78
	v_add_u32_e32 v150, s94, v124
	s_cselect_b32 s79, s29, s93
	s_cselect_b32 s78, s88, s92
	s_add_i32 s92, 0, 0x14000
	ds_read_b128 v[126:129], v150
	ds_read_b128 v[146:149], v150 offset:1024
	ds_read_b128 v[152:155], v150 offset:2048
	ds_read_b128 v[156:159], v150 offset:3072
	v_add_u32_e32 v150, s92, v124
	ds_read_b128 v[160:163], v150
	ds_read_b128 v[164:167], v150 offset:1024
	ds_read_b128 v[168:171], v150 offset:2048
	ds_read_b128 v[172:175], v150 offset:3072
	v_lshl_add_u64 v[208:209], v[122:123], 0, s[38:39]
	s_add_i32 m0, s19, 0xc000
	ds_read_b128 v[176:179], v125
	ds_read_b128 v[180:183], v125 offset:1024
	ds_read_b128 v[184:187], v125 offset:2048
	ds_read_b128 v[188:191], v125 offset:3072
	ds_read_b128 v[192:195], v125 offset:4096
	ds_read_b128 v[196:199], v125 offset:5120
	ds_read_b128 v[200:203], v125 offset:6144
	ds_read_b128 v[204:207], v125 offset:7168
	global_load_lds_dwordx4 v[208:209], off
	v_lshl_add_u64 v[208:209], v[120:121], 0, s[38:39]
	s_add_i32 m0, s19, 0xe000
	s_nop 0
	global_load_lds_dwordx4 v[208:209], off
	s_waitcnt vmcnt(8)
	s_waitcnt lgkmcnt(0)
	s_barrier
	s_setprio 1
	s_waitcnt lgkmcnt(0)
	v_mfma_f32_16x16x32_bf16 v[142:145], v[126:129], v[176:179], v[142:145]
	v_mfma_f32_16x16x32_bf16 v[138:141], v[152:155], v[176:179], v[138:141]
	v_mfma_f32_16x16x32_bf16 v[106:109], v[152:155], v[184:187], v[106:109]
	v_mfma_f32_16x16x32_bf16 v[110:113], v[126:129], v[184:187], v[110:113]
	v_mfma_f32_16x16x32_bf16 v[94:97], v[126:129], v[192:195], v[94:97]
	v_mfma_f32_16x16x32_bf16 v[90:93], v[152:155], v[192:195], v[90:93]
	v_mfma_f32_16x16x32_bf16 v[74:77], v[152:155], v[200:203], v[74:77]
	v_mfma_f32_16x16x32_bf16 v[78:81], v[126:129], v[200:203], v[78:81]
	v_mfma_f32_16x16x32_bf16 v[142:145], v[146:149], v[180:183], v[142:145]
	v_mfma_f32_16x16x32_bf16 v[138:141], v[156:159], v[180:183], v[138:141]
	v_mfma_f32_16x16x32_bf16 v[106:109], v[156:159], v[188:191], v[106:109]
	v_mfma_f32_16x16x32_bf16 v[110:113], v[146:149], v[188:191], v[110:113]
	v_mfma_f32_16x16x32_bf16 v[94:97], v[146:149], v[196:199], v[94:97]
	v_mfma_f32_16x16x32_bf16 v[90:93], v[156:159], v[196:199], v[90:93]
	v_mfma_f32_16x16x32_bf16 v[74:77], v[156:159], v[204:207], v[74:77]
	v_mfma_f32_16x16x32_bf16 v[78:81], v[146:149], v[204:207], v[78:81]
	s_setprio 0
	s_setprio 1
	v_mfma_f32_16x16x32_bf16 v[134:137], v[160:163], v[176:179], v[134:137]
	v_mfma_f32_16x16x32_bf16 v[130:133], v[168:171], v[176:179], v[130:133]
	v_mfma_f32_16x16x32_bf16 v[98:101], v[168:171], v[184:187], v[98:101]
	v_mfma_f32_16x16x32_bf16 v[102:105], v[160:163], v[184:187], v[102:105]
	v_mfma_f32_16x16x32_bf16 v[86:89], v[160:163], v[192:195], v[86:89]
	v_mfma_f32_16x16x32_bf16 v[82:85], v[168:171], v[192:195], v[82:85]
	v_mfma_f32_16x16x32_bf16 v[66:69], v[168:171], v[200:203], v[66:69]
	v_mfma_f32_16x16x32_bf16 v[70:73], v[160:163], v[200:203], v[70:73]
	v_mfma_f32_16x16x32_bf16 v[134:137], v[164:167], v[180:183], v[134:137]
	v_mfma_f32_16x16x32_bf16 v[130:133], v[172:175], v[180:183], v[130:133]
	v_mfma_f32_16x16x32_bf16 v[98:101], v[172:175], v[188:191], v[98:101]
	v_mfma_f32_16x16x32_bf16 v[102:105], v[164:167], v[188:191], v[102:105]
	v_mfma_f32_16x16x32_bf16 v[86:89], v[164:167], v[196:199], v[86:89]
	v_mfma_f32_16x16x32_bf16 v[82:85], v[172:175], v[196:199], v[82:85]
	v_mfma_f32_16x16x32_bf16 v[66:69], v[172:175], v[204:207], v[66:69]
	v_mfma_f32_16x16x32_bf16 v[70:73], v[164:167], v[204:207], v[70:73]
	s_setprio 0
	s_barrier
	s_add_i32 s93, s94, s48
	v_lshl_add_u64 v[208:209], s[78:79], 0, v[0:1]
	s_mov_b32 m0, s93
	ds_read_b128 v[176:179], v125 offset:16384
	ds_read_b128 v[180:183], v125 offset:17408
	ds_read_b128 v[184:187], v125 offset:18432
	ds_read_b128 v[188:191], v125 offset:19456
	ds_read_b128 v[192:195], v125 offset:20480
	ds_read_b128 v[196:199], v125 offset:21504
	ds_read_b128 v[200:203], v125 offset:22528
	ds_read_b128 v[204:207], v125 offset:23552
	global_load_lds_dwordx4 v[208:209], off
	s_add_i32 m0, s93, 0x2000
	s_add_u32 s94, s78, 0x80000
	v_lshl_add_u64 v[210:211], s[78:79], 0, v[114:115]
	s_addc_u32 s95, s79, 0
	s_add_i32 s92, s92, s48
	global_load_lds_dwordx4 v[210:211], off
	v_lshl_add_u64 v[212:213], s[94:95], 0, v[0:1]
	s_mov_b32 m0, s92
	v_lshl_add_u64 v[214:215], s[80:81], 0, v[114:115]
	global_load_lds_dwordx4 v[212:213], off
	v_lshl_add_u64 v[212:213], s[94:95], 0, v[114:115]
	s_add_i32 m0, s92, 0x2000
	s_nop 0
	global_load_lds_dwordx4 v[212:213], off
	v_lshl_add_u64 v[212:213], s[80:81], 0, v[0:1]
	s_mov_b32 m0, s19
	s_nop 0
	global_load_lds_dwordx4 v[212:213], off
	s_mov_b32 m0, s49
	s_nop 0
	global_load_lds_dwordx4 v[214:215], off
	s_waitcnt vmcnt(8)
	s_waitcnt lgkmcnt(0)
	s_barrier
	s_setprio 1
	s_waitcnt lgkmcnt(0)
	v_mfma_f32_16x16x32_bf16 v[62:65], v[126:129], v[176:179], v[62:65]
	v_mfma_f32_16x16x32_bf16 v[58:61], v[152:155], v[176:179], v[58:61]
	v_mfma_f32_16x16x32_bf16 v[42:45], v[152:155], v[184:187], v[42:45]
	v_mfma_f32_16x16x32_bf16 v[46:49], v[126:129], v[184:187], v[46:49]
	v_mfma_f32_16x16x32_bf16 v[30:33], v[126:129], v[192:195], v[30:33]
	v_mfma_f32_16x16x32_bf16 v[26:29], v[152:155], v[192:195], v[26:29]
	v_mfma_f32_16x16x32_bf16 v[10:13], v[152:155], v[200:203], v[10:13]
	v_mfma_f32_16x16x32_bf16 v[14:17], v[126:129], v[200:203], v[14:17]
	v_mfma_f32_16x16x32_bf16 v[62:65], v[146:149], v[180:183], v[62:65]
	v_mfma_f32_16x16x32_bf16 v[58:61], v[156:159], v[180:183], v[58:61]
	v_mfma_f32_16x16x32_bf16 v[42:45], v[156:159], v[188:191], v[42:45]
	v_mfma_f32_16x16x32_bf16 v[46:49], v[146:149], v[188:191], v[46:49]
	v_mfma_f32_16x16x32_bf16 v[30:33], v[146:149], v[196:199], v[30:33]
	v_mfma_f32_16x16x32_bf16 v[26:29], v[156:159], v[196:199], v[26:29]
	v_mfma_f32_16x16x32_bf16 v[10:13], v[156:159], v[204:207], v[10:13]
	v_mfma_f32_16x16x32_bf16 v[14:17], v[146:149], v[204:207], v[14:17]
	s_setprio 0
	s_setprio 1
	v_mfma_f32_16x16x32_bf16 v[54:57], v[160:163], v[176:179], v[54:57]
	v_mfma_f32_16x16x32_bf16 v[50:53], v[168:171], v[176:179], v[50:53]
	v_mfma_f32_16x16x32_bf16 v[34:37], v[168:171], v[184:187], v[34:37]
	v_mfma_f32_16x16x32_bf16 v[38:41], v[160:163], v[184:187], v[38:41]
	v_mfma_f32_16x16x32_bf16 v[22:25], v[160:163], v[192:195], v[22:25]
	v_mfma_f32_16x16x32_bf16 v[18:21], v[168:171], v[192:195], v[18:21]
	v_mfma_f32_16x16x32_bf16 v[2:5], v[168:171], v[200:203], v[2:5]
	v_mfma_f32_16x16x32_bf16 v[6:9], v[160:163], v[200:203], v[6:9]
	v_mfma_f32_16x16x32_bf16 v[54:57], v[164:167], v[180:183], v[54:57]
	v_mfma_f32_16x16x32_bf16 v[50:53], v[172:175], v[180:183], v[50:53]
	v_mfma_f32_16x16x32_bf16 v[34:37], v[172:175], v[188:191], v[34:37]
	v_mfma_f32_16x16x32_bf16 v[38:41], v[164:167], v[188:191], v[38:41]
	v_mfma_f32_16x16x32_bf16 v[22:25], v[164:167], v[196:199], v[22:25]
	v_mfma_f32_16x16x32_bf16 v[18:21], v[172:175], v[196:199], v[18:21]
	v_mfma_f32_16x16x32_bf16 v[2:5], v[172:175], v[204:207], v[2:5]
	v_mfma_f32_16x16x32_bf16 v[6:9], v[164:167], v[204:207], v[6:9]
	s_setprio 0
	s_barrier
	s_add_i32 s92, 0, 0x18000
	v_add_u32_e32 v150, s92, v124
	s_add_i32 s93, 0, 0x1c000
	ds_read_b128 v[126:129], v150
	ds_read_b128 v[146:149], v150 offset:1024
	ds_read_b128 v[152:155], v150 offset:2048
	ds_read_b128 v[156:159], v150 offset:3072
	v_add_u32_e32 v150, s93, v124
	ds_read_b128 v[160:163], v150
	ds_read_b128 v[164:167], v150 offset:1024
	ds_read_b128 v[168:171], v150 offset:2048
	ds_read_b128 v[172:175], v150 offset:3072
	s_add_u32 s80, s80, 0x80000
	s_addc_u32 s81, s81, 0
	s_mov_b32 m0, s61
	v_lshl_add_u64 v[216:217], s[80:81], 0, v[0:1]
	ds_read_b128 v[176:179], v125 offset:32768
	ds_read_b128 v[180:183], v125 offset:33792
	ds_read_b128 v[184:187], v125 offset:34816
	ds_read_b128 v[188:191], v125 offset:35840
	ds_read_b128 v[192:195], v125 offset:36864
	ds_read_b128 v[196:199], v125 offset:37888
	ds_read_b128 v[200:203], v125 offset:38912
	ds_read_b128 v[204:207], v125 offset:39936
	global_load_lds_dwordx4 v[216:217], off
	v_lshl_add_u64 v[216:217], s[80:81], 0, v[114:115]
	s_mov_b32 m0, s65
	s_nop 0
	global_load_lds_dwordx4 v[216:217], off
	s_waitcnt vmcnt(8)
	s_waitcnt lgkmcnt(0)
	s_barrier
	s_setprio 1
	s_waitcnt lgkmcnt(0)
	v_mfma_f32_16x16x32_bf16 v[142:145], v[126:129], v[176:179], v[142:145]
	v_mfma_f32_16x16x32_bf16 v[138:141], v[152:155], v[176:179], v[138:141]
	v_mfma_f32_16x16x32_bf16 v[106:109], v[152:155], v[184:187], v[106:109]
	v_mfma_f32_16x16x32_bf16 v[110:113], v[126:129], v[184:187], v[110:113]
	v_mfma_f32_16x16x32_bf16 v[94:97], v[126:129], v[192:195], v[94:97]
	v_mfma_f32_16x16x32_bf16 v[90:93], v[152:155], v[192:195], v[90:93]
	v_mfma_f32_16x16x32_bf16 v[74:77], v[152:155], v[200:203], v[74:77]
	v_mfma_f32_16x16x32_bf16 v[78:81], v[126:129], v[200:203], v[78:81]
	v_mfma_f32_16x16x32_bf16 v[142:145], v[146:149], v[180:183], v[142:145]
	v_mfma_f32_16x16x32_bf16 v[138:141], v[156:159], v[180:183], v[138:141]
	v_mfma_f32_16x16x32_bf16 v[106:109], v[156:159], v[188:191], v[106:109]
	v_mfma_f32_16x16x32_bf16 v[110:113], v[146:149], v[188:191], v[110:113]
	v_mfma_f32_16x16x32_bf16 v[94:97], v[146:149], v[196:199], v[94:97]
	v_mfma_f32_16x16x32_bf16 v[90:93], v[156:159], v[196:199], v[90:93]
	v_mfma_f32_16x16x32_bf16 v[74:77], v[156:159], v[204:207], v[74:77]
	v_mfma_f32_16x16x32_bf16 v[78:81], v[146:149], v[204:207], v[78:81]
	s_setprio 0
	s_setprio 1
	v_mfma_f32_16x16x32_bf16 v[134:137], v[160:163], v[176:179], v[134:137]
	v_mfma_f32_16x16x32_bf16 v[130:133], v[168:171], v[176:179], v[130:133]
	v_mfma_f32_16x16x32_bf16 v[98:101], v[168:171], v[184:187], v[98:101]
	v_mfma_f32_16x16x32_bf16 v[102:105], v[160:163], v[184:187], v[102:105]
	v_mfma_f32_16x16x32_bf16 v[86:89], v[160:163], v[192:195], v[86:89]
	v_mfma_f32_16x16x32_bf16 v[82:85], v[168:171], v[192:195], v[82:85]
	v_mfma_f32_16x16x32_bf16 v[66:69], v[168:171], v[200:203], v[66:69]
	v_mfma_f32_16x16x32_bf16 v[70:73], v[160:163], v[200:203], v[70:73]
	v_mfma_f32_16x16x32_bf16 v[134:137], v[164:167], v[180:183], v[134:137]
	v_mfma_f32_16x16x32_bf16 v[130:133], v[172:175], v[180:183], v[130:133]
	v_mfma_f32_16x16x32_bf16 v[98:101], v[172:175], v[188:191], v[98:101]
	v_mfma_f32_16x16x32_bf16 v[102:105], v[164:167], v[188:191], v[102:105]
	v_mfma_f32_16x16x32_bf16 v[86:89], v[164:167], v[196:199], v[86:89]
	v_mfma_f32_16x16x32_bf16 v[82:85], v[172:175], v[196:199], v[82:85]
	v_mfma_f32_16x16x32_bf16 v[66:69], v[172:175], v[204:207], v[66:69]
	v_mfma_f32_16x16x32_bf16 v[70:73], v[164:167], v[204:207], v[70:73]
	s_setprio 0
	s_barrier
	s_add_i32 s80, s92, s48
	v_lshl_add_u64 v[208:209], v[208:209], 0, s[54:55]
	s_mov_b32 m0, s80
	ds_read_b128 v[176:179], v125 offset:49152
	ds_read_b128 v[180:183], v125 offset:50176
	ds_read_b128 v[184:187], v125 offset:51200
	ds_read_b128 v[188:191], v125 offset:52224
	ds_read_b128 v[192:195], v125 offset:53248
	ds_read_b128 v[196:199], v125 offset:54272
	ds_read_b128 v[200:203], v125 offset:55296
	ds_read_b128 v[204:207], v125 offset:56320
	global_load_lds_dwordx4 v[208:209], off
	s_add_i32 m0, s80, 0x2000
	s_add_u32 s78, s78, 0x80080
	v_lshl_add_u64 v[208:209], v[210:211], 0, s[54:55]
	s_addc_u32 s79, s79, 0
	s_add_i32 s80, s93, s48
	global_load_lds_dwordx4 v[208:209], off
	v_lshl_add_u64 v[208:209], s[78:79], 0, v[0:1]
	s_mov_b32 m0, s80
	s_nop 0
	global_load_lds_dwordx4 v[208:209], off
	v_lshl_add_u64 v[208:209], s[78:79], 0, v[114:115]
	s_add_i32 m0, s80, 0x2000
	s_nop 0
	global_load_lds_dwordx4 v[208:209], off
	v_lshl_add_u64 v[208:209], v[212:213], 0, s[54:55]
	s_mov_b32 m0, s68
	s_nop 0
	global_load_lds_dwordx4 v[208:209], off
	v_lshl_add_u64 v[208:209], v[214:215], 0, s[54:55]
	s_mov_b32 m0, s69
	s_nop 0
	global_load_lds_dwordx4 v[208:209], off
	s_waitcnt vmcnt(8)
	s_waitcnt lgkmcnt(0)
	s_barrier
	s_setprio 1
	s_waitcnt lgkmcnt(0)
	v_mfma_f32_16x16x32_bf16 v[62:65], v[126:129], v[176:179], v[62:65]
	v_mfma_f32_16x16x32_bf16 v[58:61], v[152:155], v[176:179], v[58:61]
	v_mfma_f32_16x16x32_bf16 v[42:45], v[152:155], v[184:187], v[42:45]
	v_mfma_f32_16x16x32_bf16 v[46:49], v[126:129], v[184:187], v[46:49]
	v_mfma_f32_16x16x32_bf16 v[30:33], v[126:129], v[192:195], v[30:33]
	v_mfma_f32_16x16x32_bf16 v[26:29], v[152:155], v[192:195], v[26:29]
	v_mfma_f32_16x16x32_bf16 v[10:13], v[152:155], v[200:203], v[10:13]
	v_mfma_f32_16x16x32_bf16 v[14:17], v[126:129], v[200:203], v[14:17]
	v_mfma_f32_16x16x32_bf16 v[62:65], v[146:149], v[180:183], v[62:65]
	v_mfma_f32_16x16x32_bf16 v[58:61], v[156:159], v[180:183], v[58:61]
	v_mfma_f32_16x16x32_bf16 v[42:45], v[156:159], v[188:191], v[42:45]
	v_mfma_f32_16x16x32_bf16 v[46:49], v[146:149], v[188:191], v[46:49]
	v_mfma_f32_16x16x32_bf16 v[30:33], v[146:149], v[196:199], v[30:33]
	v_mfma_f32_16x16x32_bf16 v[26:29], v[156:159], v[196:199], v[26:29]
	v_mfma_f32_16x16x32_bf16 v[10:13], v[156:159], v[204:207], v[10:13]
	v_mfma_f32_16x16x32_bf16 v[14:17], v[146:149], v[204:207], v[14:17]
	s_setprio 0
	s_setprio 1
	v_mfma_f32_16x16x32_bf16 v[54:57], v[160:163], v[176:179], v[54:57]
	v_mfma_f32_16x16x32_bf16 v[50:53], v[168:171], v[176:179], v[50:53]
	v_mfma_f32_16x16x32_bf16 v[34:37], v[168:171], v[184:187], v[34:37]
	v_mfma_f32_16x16x32_bf16 v[38:41], v[160:163], v[184:187], v[38:41]
	v_mfma_f32_16x16x32_bf16 v[22:25], v[160:163], v[192:195], v[22:25]
	v_mfma_f32_16x16x32_bf16 v[18:21], v[168:171], v[192:195], v[18:21]
	v_mfma_f32_16x16x32_bf16 v[2:5], v[168:171], v[200:203], v[2:5]
	v_mfma_f32_16x16x32_bf16 v[6:9], v[160:163], v[200:203], v[6:9]
	v_mfma_f32_16x16x32_bf16 v[54:57], v[164:167], v[180:183], v[54:57]
	v_mfma_f32_16x16x32_bf16 v[50:53], v[172:175], v[180:183], v[50:53]
	v_mfma_f32_16x16x32_bf16 v[34:37], v[172:175], v[188:191], v[34:37]
	v_mfma_f32_16x16x32_bf16 v[38:41], v[164:167], v[188:191], v[38:41]
	v_mfma_f32_16x16x32_bf16 v[22:25], v[164:167], v[196:199], v[22:25]
	v_mfma_f32_16x16x32_bf16 v[18:21], v[172:175], v[196:199], v[18:21]
	v_mfma_f32_16x16x32_bf16 v[2:5], v[172:175], v[204:207], v[2:5]
	v_mfma_f32_16x16x32_bf16 v[6:9], v[164:167], v[204:207], v[6:9]
	s_setprio 0
	s_barrier
	s_add_i32 s89, s89, 2
	s_add_u32 s38, s38, 0x100
	s_addc_u32 s39, s39, 0
	s_cmp_gt_u32 s89, 29
	s_cbranch_scc0 .LBB0_947
	s_add_u32 s38, s72, 0xffffff00
	s_addc_u32 s39, s73, -1
	s_andn2_b64 vcc, exec, s[6:7]
	s_cbranch_vccnz .LBB0_950
	v_mov_b32_e32 v2, 0
	s_mov_b32 s16, s28
	s_mov_b32 s18, s30
	s_mov_b64 s[26:27], s[36:37]
	s_mov_b32 s70, s71
	v_mov_b32_e32 v3, v2
	v_mov_b32_e32 v4, v2
	v_mov_b32_e32 v5, v2
	v_mov_b32_e32 v6, v2
	v_mov_b32_e32 v7, v2
	v_mov_b32_e32 v8, v2
	v_mov_b32_e32 v9, v2
	v_mov_b32_e32 v18, v2
	v_mov_b32_e32 v19, v2
	v_mov_b32_e32 v20, v2
	v_mov_b32_e32 v21, v2
	v_mov_b32_e32 v22, v2
	v_mov_b32_e32 v23, v2
	v_mov_b32_e32 v24, v2
	v_mov_b32_e32 v25, v2
	v_mov_b32_e32 v34, v2
	v_mov_b32_e32 v35, v2
	v_mov_b32_e32 v36, v2
	v_mov_b32_e32 v37, v2
	v_mov_b32_e32 v38, v2
	v_mov_b32_e32 v39, v2
	v_mov_b32_e32 v40, v2
	v_mov_b32_e32 v41, v2
	v_mov_b32_e32 v50, v2
	v_mov_b32_e32 v51, v2
	v_mov_b32_e32 v52, v2
	v_mov_b32_e32 v53, v2
	v_mov_b32_e32 v54, v2
	v_mov_b32_e32 v55, v2
	v_mov_b32_e32 v56, v2
	v_mov_b32_e32 v57, v2
	v_mov_b32_e32 v10, v2
	v_mov_b32_e32 v11, v2
	v_mov_b32_e32 v12, v2
	v_mov_b32_e32 v13, v2
	v_mov_b32_e32 v14, v2
	v_mov_b32_e32 v15, v2
	v_mov_b32_e32 v16, v2
	v_mov_b32_e32 v17, v2
	v_mov_b32_e32 v26, v2
	v_mov_b32_e32 v27, v2
	v_mov_b32_e32 v28, v2
	v_mov_b32_e32 v29, v2
	v_mov_b32_e32 v30, v2
	v_mov_b32_e32 v31, v2
	v_mov_b32_e32 v32, v2
	v_mov_b32_e32 v33, v2
	v_mov_b32_e32 v42, v2
	v_mov_b32_e32 v43, v2
	v_mov_b32_e32 v44, v2
	v_mov_b32_e32 v45, v2
	v_mov_b32_e32 v46, v2
	v_mov_b32_e32 v47, v2
	v_mov_b32_e32 v48, v2
	v_mov_b32_e32 v49, v2
	v_mov_b32_e32 v58, v2
	v_mov_b32_e32 v59, v2
	v_mov_b32_e32 v60, v2
	v_mov_b32_e32 v61, v2
	v_mov_b32_e32 v62, v2
	v_mov_b32_e32 v63, v2
	v_mov_b32_e32 v64, v2
	v_mov_b32_e32 v65, v2
	v_mov_b32_e32 v66, v2
	v_mov_b32_e32 v67, v2
	v_mov_b32_e32 v68, v2
	v_mov_b32_e32 v69, v2
	v_mov_b32_e32 v70, v2
	v_mov_b32_e32 v71, v2
	v_mov_b32_e32 v72, v2
	v_mov_b32_e32 v73, v2
	v_mov_b32_e32 v82, v2
	v_mov_b32_e32 v83, v2
	v_mov_b32_e32 v84, v2
	v_mov_b32_e32 v85, v2
	v_mov_b32_e32 v86, v2
	v_mov_b32_e32 v87, v2
	v_mov_b32_e32 v88, v2
	v_mov_b32_e32 v89, v2
	v_mov_b32_e32 v98, v2
	v_mov_b32_e32 v99, v2
	v_mov_b32_e32 v100, v2
	v_mov_b32_e32 v101, v2
	v_mov_b32_e32 v102, v2
	v_mov_b32_e32 v103, v2
	v_mov_b32_e32 v104, v2
	v_mov_b32_e32 v105, v2
	v_mov_b32_e32 v130, v2
	v_mov_b32_e32 v131, v2
	v_mov_b32_e32 v132, v2
	v_mov_b32_e32 v133, v2
	v_mov_b32_e32 v134, v2
	v_mov_b32_e32 v135, v2
	v_mov_b32_e32 v136, v2
	v_mov_b32_e32 v137, v2
	v_mov_b32_e32 v74, v2
	v_mov_b32_e32 v75, v2
	v_mov_b32_e32 v76, v2
	v_mov_b32_e32 v77, v2
	v_mov_b32_e32 v78, v2
	v_mov_b32_e32 v79, v2
	v_mov_b32_e32 v80, v2
	v_mov_b32_e32 v81, v2
	v_mov_b32_e32 v90, v2
	v_mov_b32_e32 v91, v2
	v_mov_b32_e32 v92, v2
	v_mov_b32_e32 v93, v2
	v_mov_b32_e32 v94, v2
	v_mov_b32_e32 v95, v2
	v_mov_b32_e32 v96, v2
	v_mov_b32_e32 v97, v2
	v_mov_b32_e32 v106, v2
	v_mov_b32_e32 v107, v2
	v_mov_b32_e32 v108, v2
	v_mov_b32_e32 v109, v2
	v_mov_b32_e32 v110, v2
	v_mov_b32_e32 v111, v2
	v_mov_b32_e32 v112, v2
	v_mov_b32_e32 v113, v2
	v_mov_b32_e32 v138, v2
	v_mov_b32_e32 v139, v2
	v_mov_b32_e32 v140, v2
	v_mov_b32_e32 v141, v2
	v_mov_b32_e32 v142, v2
	v_mov_b32_e32 v143, v2
	v_mov_b32_e32 v144, v2
	v_mov_b32_e32 v145, v2
	s_andn2_b64 vcc, exec, s[4:5]
	s_cbranch_vccnz .LBB0_951
	s_branch .LBB0_952

.LBB0_1060:
	s_add_u32 s28, s26, 0xfff80080
	s_addc_u32 s29, s27, -1
	s_add_i32 s61, 0, 0x10000
	s_cmp_eq_u32 s49, 28
	s_cselect_b32 s31, s19, s29
	s_cselect_b32 s30, s33, s28
	v_add_u32_e32 v141, s61, v138
	s_cselect_b32 s29, s17, s48
	s_cselect_b32 s28, s44, s45
	s_add_i32 s73, 0, 0x14000
	ds_read_b128 v[142:145], v141
	ds_read_b128 v[146:149], v141 offset:1024
	ds_read_b128 v[150:153], v141 offset:2048
	ds_read_b128 v[154:157], v141 offset:3072
	v_add_u32_e32 v141, s73, v138
	ds_read_b128 v[158:161], v141
	ds_read_b128 v[162:165], v141 offset:1024
	ds_read_b128 v[166:169], v141 offset:2048
	ds_read_b128 v[170:173], v141 offset:3072
	v_lshl_add_u64 v[206:207], s[26:27], 0, v[134:135]
	s_add_i32 m0, s82, 0xc000
	ds_read_b128 v[174:177], v140
	ds_read_b128 v[178:181], v140 offset:1024
	ds_read_b128 v[182:185], v140 offset:2048
	ds_read_b128 v[186:189], v140 offset:3072
	ds_read_b128 v[190:193], v140 offset:4096
	ds_read_b128 v[194:197], v140 offset:5120
	ds_read_b128 v[198:201], v140 offset:6144
	ds_read_b128 v[202:205], v140 offset:7168
	global_load_lds_dwordx4 v[206:207], off
	v_lshl_add_u64 v[206:207], s[26:27], 0, v[132:133]
	s_add_i32 m0, s82, 0xe000
	s_nop 0
	global_load_lds_dwordx4 v[206:207], off
	s_waitcnt vmcnt(8)
	s_waitcnt lgkmcnt(0)
	s_barrier
	s_setprio 1
	s_waitcnt lgkmcnt(0)
	v_mfma_f32_16x16x32_bf16 v[126:129], v[142:145], v[174:177], v[126:129]
	v_mfma_f32_16x16x32_bf16 v[118:121], v[150:153], v[174:177], v[118:121]
	v_mfma_f32_16x16x32_bf16 v[102:105], v[150:153], v[182:185], v[102:105]
	v_mfma_f32_16x16x32_bf16 v[110:113], v[142:145], v[182:185], v[110:113]
	v_mfma_f32_16x16x32_bf16 v[94:97], v[142:145], v[190:193], v[94:97]
	v_mfma_f32_16x16x32_bf16 v[86:89], v[150:153], v[190:193], v[86:89]
	v_mfma_f32_16x16x32_bf16 v[70:73], v[150:153], v[198:201], v[70:73]
	v_mfma_f32_16x16x32_bf16 v[78:81], v[142:145], v[198:201], v[78:81]
	v_mfma_f32_16x16x32_bf16 v[126:129], v[146:149], v[178:181], v[126:129]
	v_mfma_f32_16x16x32_bf16 v[118:121], v[154:157], v[178:181], v[118:121]
	v_mfma_f32_16x16x32_bf16 v[102:105], v[154:157], v[186:189], v[102:105]
	v_mfma_f32_16x16x32_bf16 v[110:113], v[146:149], v[186:189], v[110:113]
	v_mfma_f32_16x16x32_bf16 v[94:97], v[146:149], v[194:197], v[94:97]
	v_mfma_f32_16x16x32_bf16 v[86:89], v[154:157], v[194:197], v[86:89]
	v_mfma_f32_16x16x32_bf16 v[70:73], v[154:157], v[202:205], v[70:73]
	v_mfma_f32_16x16x32_bf16 v[78:81], v[146:149], v[202:205], v[78:81]
	s_setprio 0
	s_setprio 1
	v_mfma_f32_16x16x32_bf16 v[122:125], v[158:161], v[174:177], v[122:125]
	v_mfma_f32_16x16x32_bf16 v[114:117], v[166:169], v[174:177], v[114:117]
	v_mfma_f32_16x16x32_bf16 v[98:101], v[166:169], v[182:185], v[98:101]
	v_mfma_f32_16x16x32_bf16 v[106:109], v[158:161], v[182:185], v[106:109]
	v_mfma_f32_16x16x32_bf16 v[90:93], v[158:161], v[190:193], v[90:93]
	v_mfma_f32_16x16x32_bf16 v[82:85], v[166:169], v[190:193], v[82:85]
	v_mfma_f32_16x16x32_bf16 v[66:69], v[166:169], v[198:201], v[66:69]
	v_mfma_f32_16x16x32_bf16 v[74:77], v[158:161], v[198:201], v[74:77]
	v_mfma_f32_16x16x32_bf16 v[122:125], v[162:165], v[178:181], v[122:125]
	v_mfma_f32_16x16x32_bf16 v[114:117], v[170:173], v[178:181], v[114:117]
	v_mfma_f32_16x16x32_bf16 v[98:101], v[170:173], v[186:189], v[98:101]
	v_mfma_f32_16x16x32_bf16 v[106:109], v[162:165], v[186:189], v[106:109]
	v_mfma_f32_16x16x32_bf16 v[90:93], v[162:165], v[194:197], v[90:93]
	v_mfma_f32_16x16x32_bf16 v[82:85], v[170:173], v[194:197], v[82:85]
	v_mfma_f32_16x16x32_bf16 v[66:69], v[170:173], v[202:205], v[66:69]
	v_mfma_f32_16x16x32_bf16 v[74:77], v[162:165], v[202:205], v[74:77]
	s_setprio 0
	s_barrier
	s_add_i32 s61, s61, s81
	v_lshl_add_u64 v[206:207], s[28:29], 0, v[0:1]
	s_mov_b32 m0, s61
	ds_read_b128 v[174:177], v140 offset:16384
	ds_read_b128 v[178:181], v140 offset:17408
	ds_read_b128 v[182:185], v140 offset:18432
	ds_read_b128 v[186:189], v140 offset:19456
	ds_read_b128 v[190:193], v140 offset:20480
	ds_read_b128 v[194:197], v140 offset:21504
	ds_read_b128 v[198:201], v140 offset:22528
	ds_read_b128 v[202:205], v140 offset:23552
	global_load_lds_dwordx4 v[206:207], off
	s_add_i32 m0, s61, 0x2000
	s_add_u32 s84, s28, 0x80000
	v_lshl_add_u64 v[208:209], s[28:29], 0, v[130:131]
	s_addc_u32 s85, s29, 0
	s_add_i32 s61, s73, s81
	global_load_lds_dwordx4 v[208:209], off
	v_lshl_add_u64 v[210:211], s[84:85], 0, v[0:1]
	s_mov_b32 m0, s61
	v_lshl_add_u64 v[212:213], s[30:31], 0, v[130:131]
	global_load_lds_dwordx4 v[210:211], off
	v_lshl_add_u64 v[210:211], s[84:85], 0, v[130:131]
	s_add_i32 m0, s61, 0x2000
	s_nop 0
	global_load_lds_dwordx4 v[210:211], off
	v_lshl_add_u64 v[210:211], s[30:31], 0, v[0:1]
	s_mov_b32 m0, s82
	s_nop 0
	global_load_lds_dwordx4 v[210:211], off
	s_mov_b32 m0, s68
	s_nop 0
	global_load_lds_dwordx4 v[212:213], off
	s_waitcnt vmcnt(8)
	s_waitcnt lgkmcnt(0)
	s_barrier
	s_setprio 1
	s_waitcnt lgkmcnt(0)
	v_mfma_f32_16x16x32_bf16 v[62:65], v[142:145], v[174:177], v[62:65]
	v_mfma_f32_16x16x32_bf16 v[54:57], v[150:153], v[174:177], v[54:57]
	v_mfma_f32_16x16x32_bf16 v[38:41], v[150:153], v[182:185], v[38:41]
	v_mfma_f32_16x16x32_bf16 v[46:49], v[142:145], v[182:185], v[46:49]
	v_mfma_f32_16x16x32_bf16 v[30:33], v[142:145], v[190:193], v[30:33]
	v_mfma_f32_16x16x32_bf16 v[22:25], v[150:153], v[190:193], v[22:25]
	v_mfma_f32_16x16x32_bf16 v[6:9], v[150:153], v[198:201], v[6:9]
	v_mfma_f32_16x16x32_bf16 v[14:17], v[142:145], v[198:201], v[14:17]
	v_mfma_f32_16x16x32_bf16 v[62:65], v[146:149], v[178:181], v[62:65]
	v_mfma_f32_16x16x32_bf16 v[54:57], v[154:157], v[178:181], v[54:57]
	v_mfma_f32_16x16x32_bf16 v[38:41], v[154:157], v[186:189], v[38:41]
	v_mfma_f32_16x16x32_bf16 v[46:49], v[146:149], v[186:189], v[46:49]
	v_mfma_f32_16x16x32_bf16 v[30:33], v[146:149], v[194:197], v[30:33]
	v_mfma_f32_16x16x32_bf16 v[22:25], v[154:157], v[194:197], v[22:25]
	v_mfma_f32_16x16x32_bf16 v[6:9], v[154:157], v[202:205], v[6:9]
	v_mfma_f32_16x16x32_bf16 v[14:17], v[146:149], v[202:205], v[14:17]
	s_setprio 0
	s_setprio 1
	v_mfma_f32_16x16x32_bf16 v[58:61], v[158:161], v[174:177], v[58:61]
	v_mfma_f32_16x16x32_bf16 v[50:53], v[166:169], v[174:177], v[50:53]
	v_mfma_f32_16x16x32_bf16 v[34:37], v[166:169], v[182:185], v[34:37]
	v_mfma_f32_16x16x32_bf16 v[42:45], v[158:161], v[182:185], v[42:45]
	v_mfma_f32_16x16x32_bf16 v[26:29], v[158:161], v[190:193], v[26:29]
	v_mfma_f32_16x16x32_bf16 v[18:21], v[166:169], v[190:193], v[18:21]
	v_mfma_f32_16x16x32_bf16 v[2:5], v[166:169], v[198:201], v[2:5]
	v_mfma_f32_16x16x32_bf16 v[10:13], v[158:161], v[198:201], v[10:13]
	v_mfma_f32_16x16x32_bf16 v[58:61], v[162:165], v[178:181], v[58:61]
	v_mfma_f32_16x16x32_bf16 v[50:53], v[170:173], v[178:181], v[50:53]
	v_mfma_f32_16x16x32_bf16 v[34:37], v[170:173], v[186:189], v[34:37]
	v_mfma_f32_16x16x32_bf16 v[42:45], v[162:165], v[186:189], v[42:45]
	v_mfma_f32_16x16x32_bf16 v[26:29], v[162:165], v[194:197], v[26:29]
	v_mfma_f32_16x16x32_bf16 v[18:21], v[170:173], v[194:197], v[18:21]
	v_mfma_f32_16x16x32_bf16 v[2:5], v[170:173], v[202:205], v[2:5]
	v_mfma_f32_16x16x32_bf16 v[10:13], v[162:165], v[202:205], v[10:13]
	s_setprio 0
	s_barrier
	s_add_i32 s61, 0, 0x18000
	v_add_u32_e32 v141, s61, v138
	s_add_i32 s73, 0, 0x1c000
	ds_read_b128 v[142:145], v141
	ds_read_b128 v[146:149], v141 offset:1024
	ds_read_b128 v[150:153], v141 offset:2048
	ds_read_b128 v[154:157], v141 offset:3072
	v_add_u32_e32 v141, s73, v138
	ds_read_b128 v[158:161], v141
	ds_read_b128 v[162:165], v141 offset:1024
	ds_read_b128 v[166:169], v141 offset:2048
	ds_read_b128 v[170:173], v141 offset:3072
	s_add_u32 s30, s30, 0x80000
	s_addc_u32 s31, s31, 0
	s_mov_b32 m0, s69
	v_lshl_add_u64 v[214:215], s[30:31], 0, v[0:1]
	ds_read_b128 v[174:177], v140 offset:32768
	ds_read_b128 v[178:181], v140 offset:33792
	ds_read_b128 v[182:185], v140 offset:34816
	ds_read_b128 v[186:189], v140 offset:35840
	ds_read_b128 v[190:193], v140 offset:36864
	ds_read_b128 v[194:197], v140 offset:37888
	ds_read_b128 v[198:201], v140 offset:38912
	ds_read_b128 v[202:205], v140 offset:39936
	global_load_lds_dwordx4 v[214:215], off
	v_lshl_add_u64 v[214:215], s[30:31], 0, v[130:131]
	s_mov_b32 m0, s70
	s_nop 0
	global_load_lds_dwordx4 v[214:215], off
	s_waitcnt vmcnt(8)
	s_waitcnt lgkmcnt(0)
	s_barrier
	s_setprio 1
	s_waitcnt lgkmcnt(0)
	v_mfma_f32_16x16x32_bf16 v[126:129], v[142:145], v[174:177], v[126:129]
	v_mfma_f32_16x16x32_bf16 v[118:121], v[150:153], v[174:177], v[118:121]
	v_mfma_f32_16x16x32_bf16 v[102:105], v[150:153], v[182:185], v[102:105]
	v_mfma_f32_16x16x32_bf16 v[110:113], v[142:145], v[182:185], v[110:113]
	v_mfma_f32_16x16x32_bf16 v[94:97], v[142:145], v[190:193], v[94:97]
	v_mfma_f32_16x16x32_bf16 v[86:89], v[150:153], v[190:193], v[86:89]
	v_mfma_f32_16x16x32_bf16 v[70:73], v[150:153], v[198:201], v[70:73]
	v_mfma_f32_16x16x32_bf16 v[78:81], v[142:145], v[198:201], v[78:81]
	v_mfma_f32_16x16x32_bf16 v[126:129], v[146:149], v[178:181], v[126:129]
	v_mfma_f32_16x16x32_bf16 v[118:121], v[154:157], v[178:181], v[118:121]
	v_mfma_f32_16x16x32_bf16 v[102:105], v[154:157], v[186:189], v[102:105]
	v_mfma_f32_16x16x32_bf16 v[110:113], v[146:149], v[186:189], v[110:113]
	v_mfma_f32_16x16x32_bf16 v[94:97], v[146:149], v[194:197], v[94:97]
	v_mfma_f32_16x16x32_bf16 v[86:89], v[154:157], v[194:197], v[86:89]
	v_mfma_f32_16x16x32_bf16 v[70:73], v[154:157], v[202:205], v[70:73]
	v_mfma_f32_16x16x32_bf16 v[78:81], v[146:149], v[202:205], v[78:81]
	s_setprio 0
	s_setprio 1
	v_mfma_f32_16x16x32_bf16 v[122:125], v[158:161], v[174:177], v[122:125]
	v_mfma_f32_16x16x32_bf16 v[114:117], v[166:169], v[174:177], v[114:117]
	v_mfma_f32_16x16x32_bf16 v[98:101], v[166:169], v[182:185], v[98:101]
	v_mfma_f32_16x16x32_bf16 v[106:109], v[158:161], v[182:185], v[106:109]
	v_mfma_f32_16x16x32_bf16 v[90:93], v[158:161], v[190:193], v[90:93]
	v_mfma_f32_16x16x32_bf16 v[82:85], v[166:169], v[190:193], v[82:85]
	v_mfma_f32_16x16x32_bf16 v[66:69], v[166:169], v[198:201], v[66:69]
	v_mfma_f32_16x16x32_bf16 v[74:77], v[158:161], v[198:201], v[74:77]
	v_mfma_f32_16x16x32_bf16 v[122:125], v[162:165], v[178:181], v[122:125]
	v_mfma_f32_16x16x32_bf16 v[114:117], v[170:173], v[178:181], v[114:117]
	v_mfma_f32_16x16x32_bf16 v[98:101], v[170:173], v[186:189], v[98:101]
	v_mfma_f32_16x16x32_bf16 v[106:109], v[162:165], v[186:189], v[106:109]
	v_mfma_f32_16x16x32_bf16 v[90:93], v[162:165], v[194:197], v[90:93]
	v_mfma_f32_16x16x32_bf16 v[82:85], v[170:173], v[194:197], v[82:85]
	v_mfma_f32_16x16x32_bf16 v[66:69], v[170:173], v[202:205], v[66:69]
	v_mfma_f32_16x16x32_bf16 v[74:77], v[162:165], v[202:205], v[74:77]
	s_setprio 0
	s_barrier
	s_add_i32 s30, s61, s81
	v_lshl_add_u64 v[206:207], v[206:207], 0, s[54:55]
	s_mov_b32 m0, s30
	ds_read_b128 v[174:177], v140 offset:49152
	ds_read_b128 v[178:181], v140 offset:50176
	ds_read_b128 v[182:185], v140 offset:51200
	ds_read_b128 v[186:189], v140 offset:52224
	ds_read_b128 v[190:193], v140 offset:53248
	ds_read_b128 v[194:197], v140 offset:54272
	ds_read_b128 v[198:201], v140 offset:55296
	ds_read_b128 v[202:205], v140 offset:56320
	global_load_lds_dwordx4 v[206:207], off
	s_add_i32 m0, s30, 0x2000
	s_add_u32 s28, s28, 0x80080
	v_lshl_add_u64 v[206:207], v[208:209], 0, s[54:55]
	s_addc_u32 s29, s29, 0
	s_add_i32 s30, s73, s81
	global_load_lds_dwordx4 v[206:207], off
	v_lshl_add_u64 v[206:207], s[28:29], 0, v[0:1]
	s_mov_b32 m0, s30
	s_nop 0
	global_load_lds_dwordx4 v[206:207], off
	v_lshl_add_u64 v[206:207], s[28:29], 0, v[130:131]
	s_add_i32 m0, s30, 0x2000
	s_nop 0
	global_load_lds_dwordx4 v[206:207], off
	v_lshl_add_u64 v[206:207], v[210:211], 0, s[54:55]
	s_mov_b32 m0, s71
	s_nop 0
	global_load_lds_dwordx4 v[206:207], off
	v_lshl_add_u64 v[206:207], v[212:213], 0, s[54:55]
	s_mov_b32 m0, s72
	s_nop 0
	global_load_lds_dwordx4 v[206:207], off
	s_waitcnt vmcnt(8)
	s_waitcnt lgkmcnt(0)
	s_barrier
	s_setprio 1
	s_waitcnt lgkmcnt(0)
	v_mfma_f32_16x16x32_bf16 v[62:65], v[142:145], v[174:177], v[62:65]
	v_mfma_f32_16x16x32_bf16 v[54:57], v[150:153], v[174:177], v[54:57]
	v_mfma_f32_16x16x32_bf16 v[38:41], v[150:153], v[182:185], v[38:41]
	v_mfma_f32_16x16x32_bf16 v[46:49], v[142:145], v[182:185], v[46:49]
	v_mfma_f32_16x16x32_bf16 v[30:33], v[142:145], v[190:193], v[30:33]
	v_mfma_f32_16x16x32_bf16 v[22:25], v[150:153], v[190:193], v[22:25]
	v_mfma_f32_16x16x32_bf16 v[6:9], v[150:153], v[198:201], v[6:9]
	v_mfma_f32_16x16x32_bf16 v[14:17], v[142:145], v[198:201], v[14:17]
	v_mfma_f32_16x16x32_bf16 v[62:65], v[146:149], v[178:181], v[62:65]
	v_mfma_f32_16x16x32_bf16 v[54:57], v[154:157], v[178:181], v[54:57]
	v_mfma_f32_16x16x32_bf16 v[38:41], v[154:157], v[186:189], v[38:41]
	v_mfma_f32_16x16x32_bf16 v[46:49], v[146:149], v[186:189], v[46:49]
	v_mfma_f32_16x16x32_bf16 v[30:33], v[146:149], v[194:197], v[30:33]
	v_mfma_f32_16x16x32_bf16 v[22:25], v[154:157], v[194:197], v[22:25]
	v_mfma_f32_16x16x32_bf16 v[6:9], v[154:157], v[202:205], v[6:9]
	v_mfma_f32_16x16x32_bf16 v[14:17], v[146:149], v[202:205], v[14:17]
	s_setprio 0
	s_setprio 1
	v_mfma_f32_16x16x32_bf16 v[58:61], v[158:161], v[174:177], v[58:61]
	v_mfma_f32_16x16x32_bf16 v[50:53], v[166:169], v[174:177], v[50:53]
	v_mfma_f32_16x16x32_bf16 v[34:37], v[166:169], v[182:185], v[34:37]
	v_mfma_f32_16x16x32_bf16 v[42:45], v[158:161], v[182:185], v[42:45]
	v_mfma_f32_16x16x32_bf16 v[26:29], v[158:161], v[190:193], v[26:29]
	v_mfma_f32_16x16x32_bf16 v[18:21], v[166:169], v[190:193], v[18:21]
	v_mfma_f32_16x16x32_bf16 v[2:5], v[166:169], v[198:201], v[2:5]
	v_mfma_f32_16x16x32_bf16 v[10:13], v[158:161], v[198:201], v[10:13]
	v_mfma_f32_16x16x32_bf16 v[58:61], v[162:165], v[178:181], v[58:61]
	v_mfma_f32_16x16x32_bf16 v[50:53], v[170:173], v[178:181], v[50:53]
	v_mfma_f32_16x16x32_bf16 v[34:37], v[170:173], v[186:189], v[34:37]
	v_mfma_f32_16x16x32_bf16 v[42:45], v[162:165], v[186:189], v[42:45]
	v_mfma_f32_16x16x32_bf16 v[26:29], v[162:165], v[194:197], v[26:29]
	v_mfma_f32_16x16x32_bf16 v[18:21], v[170:173], v[194:197], v[18:21]
	v_mfma_f32_16x16x32_bf16 v[2:5], v[170:173], v[202:205], v[2:5]
	v_mfma_f32_16x16x32_bf16 v[10:13], v[162:165], v[202:205], v[10:13]
	s_setprio 0
	s_barrier
	s_add_i32 s49, s49, 2
	s_add_u32 s45, s45, 0x100
	s_addc_u32 s48, s48, 0
	s_add_u32 s26, s26, 0x100
	s_addc_u32 s27, s27, 0
	s_cmp_gt_u32 s49, 29
	s_cbranch_scc0 .LBB0_1060
	s_and_b64 vcc, exec, s[14:15]
	s_cbranch_vccz .LBB0_1063
	s_barrier

.LBB0_1200:
	s_add_u32 s28, s18, s22
	s_addc_u32 s29, s19, s23
	s_add_u32 s28, s28, 0x100
	s_addc_u32 s29, s29, 0
	s_add_u32 s78, s74, s22
	s_addc_u32 s79, s75, s23
	s_add_i32 s80, 0, 0x10000
	s_cmpk_eq_i32 s22, 0x2b00
	s_cselect_b32 s31, s21, s29
	s_cselect_b32 s30, s20, s28
	s_cselect_b32 s29, s9, s79
	s_cselect_b32 s28, s8, s78
	s_add_i32 s81, 0, 0x14000
	v_add_u32_e32 v154, s80, v140
	v_add_u32_e32 v170, s81, v140
	ds_read_b128 v[142:145], v154
	ds_read_b128 v[146:149], v154 offset:1024
	ds_read_b128 v[150:153], v154 offset:2048
	ds_read_b128 v[154:157], v154 offset:3072
	ds_read_b128 v[158:161], v170
	ds_read_b128 v[162:165], v170 offset:1024
	ds_read_b128 v[166:169], v170 offset:2048
	ds_read_b128 v[170:173], v170 offset:3072
	v_lshl_add_u64 v[206:207], v[138:139], 0, s[22:23]
	s_add_i32 m0, s61, 0xc000
	ds_read_b128 v[174:177], v141
	ds_read_b128 v[178:181], v141 offset:1024
	ds_read_b128 v[182:185], v141 offset:2048
	ds_read_b128 v[186:189], v141 offset:3072
	ds_read_b128 v[190:193], v141 offset:4096
	ds_read_b128 v[194:197], v141 offset:5120
	ds_read_b128 v[198:201], v141 offset:6144
	ds_read_b128 v[202:205], v141 offset:7168
	global_load_lds_dwordx4 v[206:207], off
	v_lshl_add_u64 v[206:207], v[136:137], 0, s[22:23]
	s_add_i32 m0, s61, 0xe000
	s_nop 0
	global_load_lds_dwordx4 v[206:207], off
	s_waitcnt vmcnt(8)
	s_waitcnt lgkmcnt(0)
	s_barrier
	s_setprio 1
	s_waitcnt lgkmcnt(0)
	v_mfma_f32_16x16x32_bf16 v[126:129], v[142:145], v[174:177], v[126:129]
	v_mfma_f32_16x16x32_bf16 v[122:125], v[150:153], v[174:177], v[122:125]
	v_mfma_f32_16x16x32_bf16 v[106:109], v[150:153], v[182:185], v[106:109]
	v_mfma_f32_16x16x32_bf16 v[110:113], v[142:145], v[182:185], v[110:113]
	v_mfma_f32_16x16x32_bf16 v[98:101], v[142:145], v[190:193], v[98:101]
	v_mfma_f32_16x16x32_bf16 v[90:93], v[150:153], v[190:193], v[90:93]
	v_mfma_f32_16x16x32_bf16 v[74:77], v[150:153], v[198:201], v[74:77]
	v_mfma_f32_16x16x32_bf16 v[82:85], v[142:145], v[198:201], v[82:85]
	v_mfma_f32_16x16x32_bf16 v[126:129], v[146:149], v[178:181], v[126:129]
	v_mfma_f32_16x16x32_bf16 v[122:125], v[154:157], v[178:181], v[122:125]
	v_mfma_f32_16x16x32_bf16 v[106:109], v[154:157], v[186:189], v[106:109]
	v_mfma_f32_16x16x32_bf16 v[110:113], v[146:149], v[186:189], v[110:113]
	v_mfma_f32_16x16x32_bf16 v[98:101], v[146:149], v[194:197], v[98:101]
	v_mfma_f32_16x16x32_bf16 v[90:93], v[154:157], v[194:197], v[90:93]
	v_mfma_f32_16x16x32_bf16 v[74:77], v[154:157], v[202:205], v[74:77]
	v_mfma_f32_16x16x32_bf16 v[82:85], v[146:149], v[202:205], v[82:85]
	s_setprio 0
	s_setprio 1
	v_mfma_f32_16x16x32_bf16 v[118:121], v[158:161], v[174:177], v[118:121]
	v_mfma_f32_16x16x32_bf16 v[114:117], v[166:169], v[174:177], v[114:117]
	v_mfma_f32_16x16x32_bf16 v[94:97], v[166:169], v[182:185], v[94:97]
	v_mfma_f32_16x16x32_bf16 v[102:105], v[158:161], v[182:185], v[102:105]
	v_mfma_f32_16x16x32_bf16 v[86:89], v[158:161], v[190:193], v[86:89]
	v_mfma_f32_16x16x32_bf16 v[78:81], v[166:169], v[190:193], v[78:81]
	v_mfma_f32_16x16x32_bf16 v[66:69], v[166:169], v[198:201], v[66:69]
	v_mfma_f32_16x16x32_bf16 v[70:73], v[158:161], v[198:201], v[70:73]
	v_mfma_f32_16x16x32_bf16 v[118:121], v[162:165], v[178:181], v[118:121]
	v_mfma_f32_16x16x32_bf16 v[114:117], v[170:173], v[178:181], v[114:117]
	v_mfma_f32_16x16x32_bf16 v[94:97], v[170:173], v[186:189], v[94:97]
	v_mfma_f32_16x16x32_bf16 v[102:105], v[162:165], v[186:189], v[102:105]
	v_mfma_f32_16x16x32_bf16 v[86:89], v[162:165], v[194:197], v[86:89]
	v_mfma_f32_16x16x32_bf16 v[78:81], v[170:173], v[194:197], v[78:81]
	v_mfma_f32_16x16x32_bf16 v[66:69], v[170:173], v[202:205], v[66:69]
	v_mfma_f32_16x16x32_bf16 v[70:73], v[162:165], v[202:205], v[70:73]
	s_setprio 0
	s_barrier
	s_add_i32 s78, s80, s44
	v_lshl_add_u64 v[206:207], s[28:29], 0, v[0:1]
	s_mov_b32 m0, s78
	ds_read_b128 v[174:177], v141 offset:16384
	ds_read_b128 v[178:181], v141 offset:17408
	ds_read_b128 v[182:185], v141 offset:18432
	ds_read_b128 v[186:189], v141 offset:19456
	ds_read_b128 v[190:193], v141 offset:20480
	ds_read_b128 v[194:197], v141 offset:21504
	ds_read_b128 v[198:201], v141 offset:22528
	ds_read_b128 v[202:205], v141 offset:23552
	global_load_lds_dwordx4 v[206:207], off
	s_add_i32 m0, s78, 0x2000
	s_add_u32 s78, s28, 0x160000
	v_lshl_add_u64 v[208:209], s[28:29], 0, v[130:131]
	s_addc_u32 s79, s29, 0
	s_add_i32 s80, s81, s44
	global_load_lds_dwordx4 v[208:209], off
	v_lshl_add_u64 v[214:215], s[78:79], 0, v[0:1]
	s_mov_b32 m0, s80
	v_lshl_add_u64 v[216:217], s[30:31], 0, v[130:131]
	global_load_lds_dwordx4 v[214:215], off
	v_lshl_add_u64 v[214:215], s[78:79], 0, v[130:131]
	s_add_i32 m0, s80, 0x2000
	s_nop 0
	global_load_lds_dwordx4 v[214:215], off
	v_lshl_add_u64 v[214:215], s[30:31], 0, v[0:1]
	s_mov_b32 m0, s61
	s_nop 0
	global_load_lds_dwordx4 v[214:215], off
	s_mov_b32 m0, s65
	s_nop 0
	global_load_lds_dwordx4 v[216:217], off
	s_waitcnt vmcnt(8)
	s_waitcnt lgkmcnt(0)
	s_barrier
	s_setprio 1
	s_waitcnt lgkmcnt(0)
	v_mfma_f32_16x16x32_bf16 v[62:65], v[142:145], v[174:177], v[62:65]
	v_mfma_f32_16x16x32_bf16 v[58:61], v[150:153], v[174:177], v[58:61]
	v_mfma_f32_16x16x32_bf16 v[42:45], v[150:153], v[182:185], v[42:45]
	v_mfma_f32_16x16x32_bf16 v[50:53], v[142:145], v[182:185], v[50:53]
	v_mfma_f32_16x16x32_bf16 v[34:37], v[142:145], v[190:193], v[34:37]
	v_mfma_f32_16x16x32_bf16 v[26:29], v[150:153], v[190:193], v[26:29]
	v_mfma_f32_16x16x32_bf16 v[10:13], v[150:153], v[198:201], v[10:13]
	v_mfma_f32_16x16x32_bf16 v[18:21], v[142:145], v[198:201], v[18:21]
	v_mfma_f32_16x16x32_bf16 v[62:65], v[146:149], v[178:181], v[62:65]
	v_mfma_f32_16x16x32_bf16 v[58:61], v[154:157], v[178:181], v[58:61]
	v_mfma_f32_16x16x32_bf16 v[42:45], v[154:157], v[186:189], v[42:45]
	v_mfma_f32_16x16x32_bf16 v[50:53], v[146:149], v[186:189], v[50:53]
	v_mfma_f32_16x16x32_bf16 v[34:37], v[146:149], v[194:197], v[34:37]
	v_mfma_f32_16x16x32_bf16 v[26:29], v[154:157], v[194:197], v[26:29]
	v_mfma_f32_16x16x32_bf16 v[10:13], v[154:157], v[202:205], v[10:13]
	v_mfma_f32_16x16x32_bf16 v[18:21], v[146:149], v[202:205], v[18:21]
	s_setprio 0
	s_setprio 1
	v_mfma_f32_16x16x32_bf16 v[54:57], v[158:161], v[174:177], v[54:57]
	v_mfma_f32_16x16x32_bf16 v[46:49], v[166:169], v[174:177], v[46:49]
	v_mfma_f32_16x16x32_bf16 v[30:33], v[166:169], v[182:185], v[30:33]
	v_mfma_f32_16x16x32_bf16 v[38:41], v[158:161], v[182:185], v[38:41]
	v_mfma_f32_16x16x32_bf16 v[22:25], v[158:161], v[190:193], v[22:25]
	v_mfma_f32_16x16x32_bf16 v[14:17], v[166:169], v[190:193], v[14:17]
	v_mfma_f32_16x16x32_bf16 v[2:5], v[166:169], v[198:201], v[2:5]
	v_mfma_f32_16x16x32_bf16 v[6:9], v[158:161], v[198:201], v[6:9]
	v_mfma_f32_16x16x32_bf16 v[54:57], v[162:165], v[178:181], v[54:57]
	v_mfma_f32_16x16x32_bf16 v[46:49], v[170:173], v[178:181], v[46:49]
	v_mfma_f32_16x16x32_bf16 v[30:33], v[170:173], v[186:189], v[30:33]
	v_mfma_f32_16x16x32_bf16 v[38:41], v[162:165], v[186:189], v[38:41]
	v_mfma_f32_16x16x32_bf16 v[22:25], v[162:165], v[194:197], v[22:25]
	v_mfma_f32_16x16x32_bf16 v[14:17], v[170:173], v[194:197], v[14:17]
	v_mfma_f32_16x16x32_bf16 v[2:5], v[170:173], v[202:205], v[2:5]
	v_mfma_f32_16x16x32_bf16 v[6:9], v[162:165], v[202:205], v[6:9]
	s_setprio 0
	s_barrier
	s_add_i32 s78, 0, 0x18000
	s_add_i32 s79, 0, 0x1c000
	v_add_u32_e32 v154, s78, v140
	v_add_u32_e32 v170, s79, v140
	ds_read_b128 v[142:145], v154
	ds_read_b128 v[146:149], v154 offset:1024
	ds_read_b128 v[150:153], v154 offset:2048
	ds_read_b128 v[154:157], v154 offset:3072
	ds_read_b128 v[158:161], v170
	ds_read_b128 v[162:165], v170 offset:1024
	ds_read_b128 v[166:169], v170 offset:2048
	ds_read_b128 v[170:173], v170 offset:3072
	s_add_u32 s30, s30, 0x160000
	s_addc_u32 s31, s31, 0
	s_mov_b32 m0, s66
	v_lshl_add_u64 v[218:219], s[30:31], 0, v[0:1]
	ds_read_b128 v[174:177], v141 offset:32768
	ds_read_b128 v[178:181], v141 offset:33792
	ds_read_b128 v[182:185], v141 offset:34816
	ds_read_b128 v[186:189], v141 offset:35840
	ds_read_b128 v[190:193], v141 offset:36864
	ds_read_b128 v[194:197], v141 offset:37888
	ds_read_b128 v[198:201], v141 offset:38912
	ds_read_b128 v[202:205], v141 offset:39936
	global_load_lds_dwordx4 v[218:219], off
	v_lshl_add_u64 v[218:219], s[30:31], 0, v[130:131]
	s_mov_b32 m0, s67
	s_nop 0
	global_load_lds_dwordx4 v[218:219], off
	s_waitcnt vmcnt(8)
	s_waitcnt lgkmcnt(0)
	s_barrier
	s_setprio 1
	s_waitcnt lgkmcnt(0)
	v_mfma_f32_16x16x32_bf16 v[126:129], v[142:145], v[174:177], v[126:129]
	v_mfma_f32_16x16x32_bf16 v[122:125], v[150:153], v[174:177], v[122:125]
	v_mfma_f32_16x16x32_bf16 v[106:109], v[150:153], v[182:185], v[106:109]
	v_mfma_f32_16x16x32_bf16 v[110:113], v[142:145], v[182:185], v[110:113]
	v_mfma_f32_16x16x32_bf16 v[98:101], v[142:145], v[190:193], v[98:101]
	v_mfma_f32_16x16x32_bf16 v[90:93], v[150:153], v[190:193], v[90:93]
	v_mfma_f32_16x16x32_bf16 v[74:77], v[150:153], v[198:201], v[74:77]
	v_mfma_f32_16x16x32_bf16 v[82:85], v[142:145], v[198:201], v[82:85]
	v_mfma_f32_16x16x32_bf16 v[126:129], v[146:149], v[178:181], v[126:129]
	v_mfma_f32_16x16x32_bf16 v[122:125], v[154:157], v[178:181], v[122:125]
	v_mfma_f32_16x16x32_bf16 v[106:109], v[154:157], v[186:189], v[106:109]
	v_mfma_f32_16x16x32_bf16 v[110:113], v[146:149], v[186:189], v[110:113]
	v_mfma_f32_16x16x32_bf16 v[98:101], v[146:149], v[194:197], v[98:101]
	v_mfma_f32_16x16x32_bf16 v[90:93], v[154:157], v[194:197], v[90:93]
	v_mfma_f32_16x16x32_bf16 v[74:77], v[154:157], v[202:205], v[74:77]
	v_mfma_f32_16x16x32_bf16 v[82:85], v[146:149], v[202:205], v[82:85]
	s_setprio 0
	s_setprio 1
	v_mfma_f32_16x16x32_bf16 v[118:121], v[158:161], v[174:177], v[118:121]
	v_mfma_f32_16x16x32_bf16 v[114:117], v[166:169], v[174:177], v[114:117]
	v_mfma_f32_16x16x32_bf16 v[94:97], v[166:169], v[182:185], v[94:97]
	v_mfma_f32_16x16x32_bf16 v[102:105], v[158:161], v[182:185], v[102:105]
	v_mfma_f32_16x16x32_bf16 v[86:89], v[158:161], v[190:193], v[86:89]
	v_mfma_f32_16x16x32_bf16 v[78:81], v[166:169], v[190:193], v[78:81]
	v_mfma_f32_16x16x32_bf16 v[66:69], v[166:169], v[198:201], v[66:69]
	v_mfma_f32_16x16x32_bf16 v[70:73], v[158:161], v[198:201], v[70:73]
	v_mfma_f32_16x16x32_bf16 v[118:121], v[162:165], v[178:181], v[118:121]
	v_mfma_f32_16x16x32_bf16 v[114:117], v[170:173], v[178:181], v[114:117]
	v_mfma_f32_16x16x32_bf16 v[94:97], v[170:173], v[186:189], v[94:97]
	v_mfma_f32_16x16x32_bf16 v[102:105], v[162:165], v[186:189], v[102:105]
	v_mfma_f32_16x16x32_bf16 v[86:89], v[162:165], v[194:197], v[86:89]
	v_mfma_f32_16x16x32_bf16 v[78:81], v[170:173], v[194:197], v[78:81]
	v_mfma_f32_16x16x32_bf16 v[66:69], v[170:173], v[202:205], v[66:69]
	v_mfma_f32_16x16x32_bf16 v[70:73], v[162:165], v[202:205], v[70:73]
	s_setprio 0
	s_barrier
	s_add_i32 s30, s78, s44
	v_lshl_add_u64 v[206:207], v[206:207], 0, s[54:55]
	s_mov_b32 m0, s30
	ds_read_b128 v[174:177], v141 offset:49152
	ds_read_b128 v[178:181], v141 offset:50176
	ds_read_b128 v[182:185], v141 offset:51200
	ds_read_b128 v[186:189], v141 offset:52224
	ds_read_b128 v[190:193], v141 offset:53248
	ds_read_b128 v[194:197], v141 offset:54272
	ds_read_b128 v[198:201], v141 offset:55296
	ds_read_b128 v[202:205], v141 offset:56320
	global_load_lds_dwordx4 v[206:207], off
	s_add_i32 m0, s30, 0x2000
	s_add_u32 s28, s28, 0x160080
	v_lshl_add_u64 v[206:207], v[208:209], 0, s[54:55]
	s_addc_u32 s29, s29, 0
	s_add_i32 s30, s79, s44
	global_load_lds_dwordx4 v[206:207], off
	v_lshl_add_u64 v[206:207], s[28:29], 0, v[0:1]
	s_mov_b32 m0, s30
	s_nop 0
	global_load_lds_dwordx4 v[206:207], off
	v_lshl_add_u64 v[206:207], s[28:29], 0, v[130:131]
	s_add_i32 m0, s30, 0x2000
	s_nop 0
	global_load_lds_dwordx4 v[206:207], off
	v_lshl_add_u64 v[206:207], v[214:215], 0, s[54:55]
	s_mov_b32 m0, s68
	s_nop 0
	global_load_lds_dwordx4 v[206:207], off
	v_lshl_add_u64 v[206:207], v[216:217], 0, s[54:55]
	s_mov_b32 m0, s69
	s_nop 0
	global_load_lds_dwordx4 v[206:207], off
	s_waitcnt vmcnt(8)
	s_waitcnt lgkmcnt(0)
	s_barrier
	s_setprio 1
	s_waitcnt lgkmcnt(0)
	v_mfma_f32_16x16x32_bf16 v[62:65], v[142:145], v[174:177], v[62:65]
	v_mfma_f32_16x16x32_bf16 v[58:61], v[150:153], v[174:177], v[58:61]
	v_mfma_f32_16x16x32_bf16 v[42:45], v[150:153], v[182:185], v[42:45]
	v_mfma_f32_16x16x32_bf16 v[50:53], v[142:145], v[182:185], v[50:53]
	v_mfma_f32_16x16x32_bf16 v[34:37], v[142:145], v[190:193], v[34:37]
	v_mfma_f32_16x16x32_bf16 v[26:29], v[150:153], v[190:193], v[26:29]
	v_mfma_f32_16x16x32_bf16 v[10:13], v[150:153], v[198:201], v[10:13]
	v_mfma_f32_16x16x32_bf16 v[18:21], v[142:145], v[198:201], v[18:21]
	v_mfma_f32_16x16x32_bf16 v[62:65], v[146:149], v[178:181], v[62:65]
	v_mfma_f32_16x16x32_bf16 v[58:61], v[154:157], v[178:181], v[58:61]
	v_mfma_f32_16x16x32_bf16 v[42:45], v[154:157], v[186:189], v[42:45]
	v_mfma_f32_16x16x32_bf16 v[50:53], v[146:149], v[186:189], v[50:53]
	v_mfma_f32_16x16x32_bf16 v[34:37], v[146:149], v[194:197], v[34:37]
	v_mfma_f32_16x16x32_bf16 v[26:29], v[154:157], v[194:197], v[26:29]
	v_mfma_f32_16x16x32_bf16 v[10:13], v[154:157], v[202:205], v[10:13]
	v_mfma_f32_16x16x32_bf16 v[18:21], v[146:149], v[202:205], v[18:21]
	s_setprio 0
	s_setprio 1
	v_mfma_f32_16x16x32_bf16 v[54:57], v[158:161], v[174:177], v[54:57]
	v_mfma_f32_16x16x32_bf16 v[46:49], v[166:169], v[174:177], v[46:49]
	v_mfma_f32_16x16x32_bf16 v[30:33], v[166:169], v[182:185], v[30:33]
	v_mfma_f32_16x16x32_bf16 v[38:41], v[158:161], v[182:185], v[38:41]
	v_mfma_f32_16x16x32_bf16 v[22:25], v[158:161], v[190:193], v[22:25]
	v_mfma_f32_16x16x32_bf16 v[14:17], v[166:169], v[190:193], v[14:17]
	v_mfma_f32_16x16x32_bf16 v[2:5], v[166:169], v[198:201], v[2:5]
	v_mfma_f32_16x16x32_bf16 v[6:9], v[158:161], v[198:201], v[6:9]
	v_mfma_f32_16x16x32_bf16 v[54:57], v[162:165], v[178:181], v[54:57]
	v_mfma_f32_16x16x32_bf16 v[46:49], v[170:173], v[178:181], v[46:49]
	v_mfma_f32_16x16x32_bf16 v[30:33], v[170:173], v[186:189], v[30:33]
	v_mfma_f32_16x16x32_bf16 v[38:41], v[162:165], v[186:189], v[38:41]
	v_mfma_f32_16x16x32_bf16 v[22:25], v[162:165], v[194:197], v[22:25]
	v_mfma_f32_16x16x32_bf16 v[14:17], v[170:173], v[194:197], v[14:17]
	v_mfma_f32_16x16x32_bf16 v[2:5], v[170:173], v[202:205], v[2:5]
	v_mfma_f32_16x16x32_bf16 v[6:9], v[162:165], v[202:205], v[6:9]
	s_setprio 0
	s_barrier
	s_add_i32 s76, s76, 2
	s_add_u32 s22, s22, 0x100
	s_addc_u32 s23, s23, 0
	s_cmpk_gt_u32 s76, 0x55
	s_cbranch_scc0 .LBB0_1200
	s_add_u32 s22, s74, 0xffffff00
	s_addc_u32 s23, s75, -1
	s_and_b64 vcc, exec, s[6:7]
	s_cbranch_vccnz .LBB0_1203
	v_mov_b32_e32 v2, 0
	s_mov_b32 s16, s71
	s_mov_b32 s39, s72
	s_mov_b64 s[18:19], s[20:21]
	s_mov_b32 s70, s73
	v_mov_b32_e32 v3, v2
	v_mov_b32_e32 v4, v2
	v_mov_b32_e32 v5, v2
	v_mov_b32_e32 v6, v2
	v_mov_b32_e32 v7, v2
	v_mov_b32_e32 v8, v2
	v_mov_b32_e32 v9, v2
	v_mov_b32_e32 v14, v2
	v_mov_b32_e32 v15, v2
	v_mov_b32_e32 v16, v2
	v_mov_b32_e32 v17, v2
	v_mov_b32_e32 v22, v2
	v_mov_b32_e32 v23, v2
	v_mov_b32_e32 v24, v2
	v_mov_b32_e32 v25, v2
	v_mov_b32_e32 v30, v2
	v_mov_b32_e32 v31, v2
	v_mov_b32_e32 v32, v2
	v_mov_b32_e32 v33, v2
	v_mov_b32_e32 v38, v2
	v_mov_b32_e32 v39, v2
	v_mov_b32_e32 v40, v2
	v_mov_b32_e32 v41, v2
	v_mov_b32_e32 v46, v2
	v_mov_b32_e32 v47, v2
	v_mov_b32_e32 v48, v2
	v_mov_b32_e32 v49, v2
	v_mov_b32_e32 v54, v2
	v_mov_b32_e32 v55, v2
	v_mov_b32_e32 v56, v2
	v_mov_b32_e32 v57, v2
	v_mov_b32_e32 v10, v2
	v_mov_b32_e32 v11, v2
	v_mov_b32_e32 v12, v2
	v_mov_b32_e32 v13, v2
	v_mov_b32_e32 v18, v2
	v_mov_b32_e32 v19, v2
	v_mov_b32_e32 v20, v2
	v_mov_b32_e32 v21, v2
	v_mov_b32_e32 v26, v2
	v_mov_b32_e32 v27, v2
	v_mov_b32_e32 v28, v2
	v_mov_b32_e32 v29, v2
	v_mov_b32_e32 v34, v2
	v_mov_b32_e32 v35, v2
	v_mov_b32_e32 v36, v2
	v_mov_b32_e32 v37, v2
	v_mov_b32_e32 v42, v2
	v_mov_b32_e32 v43, v2
	v_mov_b32_e32 v44, v2
	v_mov_b32_e32 v45, v2
	v_mov_b32_e32 v50, v2
	v_mov_b32_e32 v51, v2
	v_mov_b32_e32 v52, v2
	v_mov_b32_e32 v53, v2
	v_mov_b32_e32 v58, v2
	v_mov_b32_e32 v59, v2
	v_mov_b32_e32 v60, v2
	v_mov_b32_e32 v61, v2
	v_mov_b32_e32 v62, v2
	v_mov_b32_e32 v63, v2
	v_mov_b32_e32 v64, v2
	v_mov_b32_e32 v65, v2
	v_mov_b32_e32 v66, v2
	v_mov_b32_e32 v67, v2
	v_mov_b32_e32 v68, v2
	v_mov_b32_e32 v69, v2
	v_mov_b32_e32 v70, v2
	v_mov_b32_e32 v71, v2
	v_mov_b32_e32 v72, v2
	v_mov_b32_e32 v73, v2
	v_mov_b32_e32 v78, v2
	v_mov_b32_e32 v79, v2
	v_mov_b32_e32 v80, v2
	v_mov_b32_e32 v81, v2
	v_mov_b32_e32 v86, v2
	v_mov_b32_e32 v87, v2
	v_mov_b32_e32 v88, v2
	v_mov_b32_e32 v89, v2
	v_mov_b32_e32 v94, v2
	v_mov_b32_e32 v95, v2
	v_mov_b32_e32 v96, v2
	v_mov_b32_e32 v97, v2
	v_mov_b32_e32 v102, v2
	v_mov_b32_e32 v103, v2
	v_mov_b32_e32 v104, v2
	v_mov_b32_e32 v105, v2
	v_mov_b32_e32 v114, v2
	v_mov_b32_e32 v115, v2
	v_mov_b32_e32 v116, v2
	v_mov_b32_e32 v117, v2
	v_mov_b32_e32 v118, v2
	v_mov_b32_e32 v119, v2
	v_mov_b32_e32 v120, v2
	v_mov_b32_e32 v121, v2
	v_mov_b32_e32 v74, v2
	v_mov_b32_e32 v75, v2
	v_mov_b32_e32 v76, v2
	v_mov_b32_e32 v77, v2
	v_mov_b32_e32 v82, v2
	v_mov_b32_e32 v83, v2
	v_mov_b32_e32 v84, v2
	v_mov_b32_e32 v85, v2
	v_mov_b32_e32 v90, v2
	v_mov_b32_e32 v91, v2
	v_mov_b32_e32 v92, v2
	v_mov_b32_e32 v93, v2
	v_mov_b32_e32 v98, v2
	v_mov_b32_e32 v99, v2
	v_mov_b32_e32 v100, v2
	v_mov_b32_e32 v101, v2
	v_mov_b32_e32 v106, v2
	v_mov_b32_e32 v107, v2
	v_mov_b32_e32 v108, v2
	v_mov_b32_e32 v109, v2
	v_mov_b32_e32 v110, v2
	v_mov_b32_e32 v111, v2
	v_mov_b32_e32 v112, v2
	v_mov_b32_e32 v113, v2
	v_mov_b32_e32 v122, v2
	v_mov_b32_e32 v123, v2
	v_mov_b32_e32 v124, v2
	v_mov_b32_e32 v125, v2
	v_mov_b32_e32 v126, v2
	v_mov_b32_e32 v127, v2
	v_mov_b32_e32 v128, v2
	v_mov_b32_e32 v129, v2
	s_andn2_b64 vcc, exec, s[4:5]
	s_cbranch_vccnz .LBB0_1204
	s_branch .LBB0_1205
